# v29 + attention block epilogue: xor-1 shuffles via DPP quad_perm instead of ds_bpermute, dword stores as global (no per-store LDS/lgkm wait)
# speedup vs baseline: 1.0038x; 1.0038x over previous
; #define SBAR() __builtin_amdgcn_sched_barrier(0)
; __device__ __forceinline__ int crow(int r, int hi) { return (r & 3) + 8 * (r >> 2) + 4 * hi; }
; #define SEAM_K0() do { VMWN(8); SWRITE_HK(0); SBAR(); } while (0)
; __device__ __forceinline__ bool fox_block(const BlockRef& cur, BlockRef& nxt, unsigned* ctr, const unsigned* nrm, bf16_t* PROJ, bf16_t* MIX, char* lds, Seam& S, const float* __restrict__ CF, const float* __restrict__ fnorm) {
;     ...
;     SBAR(); SEAM_K0();
;     if (hi == 0) li_l[r32] = l_reg; asm volatile("s_waitcnt lgkmcnt(0)" ::: "memory");
;     float rs[16];
; #pragma unroll
;     for (int r = 0; r < 16; ++r) { const float rl = __builtin_amdgcn_rcpf(li_l[crow(r, hi)]); float a = 0.f;
; #pragma unroll
;         for (int d0 = 0; d0 < 4; ++d0) { const float v = o[d0][r] * rl; o[d0][r] = v; a += v * v; }
;         a += __shfl_xor(a, 1); a += __shfl_xor(a, 2); a += __shfl_xor(a, 4); a += __shfl_xor(a, 8); a += __shfl_xor(a, 16);
;         rs[r] = rsqrtf(a * (1.f / 128.f) + RMS_EPS); }
.LBB0_822:
	s_ashr_i32 s73, s72, 31
	s_waitcnt vmcnt(8)
	s_waitcnt vmcnt(0) lgkmcnt(0)
	ds_write_b128 v213, v[102:105] offset:32768
	ds_write_b128 v213, v[110:113] offset:40960
	v_cmp_gt_u32_e32 vcc, 32, v214
	s_and_saveexec_b64 s[10:11], vcc
	ds_write_b32 v215, v114
	s_or_b64 exec, exec, s[10:11]
	v_and_b32_e32 v67, 64, v207
	v_xor_b32_e32 v66, 1, v207
	v_add_u32_e32 v67, 64, v67
	v_cmp_lt_i32_e32 vcc, v66, v67
	s_waitcnt lgkmcnt(0)
	v_mov_b32_e32 v74, v50
	v_mov_b32_e32 v75, v34
	v_cndmask_b32_e32 v66, v207, v66, vcc
	v_lshlrev_b32_e32 v116, 2, v66
	v_xor_b32_e32 v66, 2, v207
	v_cmp_lt_i32_e32 vcc, v66, v67
	v_mov_b32_e32 v34, v51
	v_lshl_or_b32 v196, s22, 7, v211
	v_cndmask_b32_e32 v66, v207, v66, vcc
	v_lshlrev_b32_e32 v118, 2, v66
	v_xor_b32_e32 v66, 4, v207
	v_cmp_lt_i32_e32 vcc, v66, v67
	s_nop 1
	v_cndmask_b32_e32 v66, v207, v66, vcc
	v_lshlrev_b32_e32 v119, 2, v66
	v_xor_b32_e32 v66, 8, v207
	v_cmp_lt_i32_e32 vcc, v66, v67
	s_nop 1
	v_cndmask_b32_e32 v66, v207, v66, vcc
	v_lshlrev_b32_e32 v120, 2, v66
	v_xor_b32_e32 v66, 16, v207
	v_cmp_lt_i32_e32 vcc, v66, v67
	s_nop 1
	v_cndmask_b32_e32 v66, v207, v66, vcc
	v_lshlrev_b32_e32 v121, 2, v66
	ds_read_b128 v[70:73], v212
	ds_read_b128 v[66:69], v212 offset:32
	s_waitcnt lgkmcnt(0)
	v_rcp_f32_e32 v70, v70
	s_nop 0
	v_pk_mul_f32 v[86:87], v[74:75], v[70:71] op_sel_hi:[1,0]
	v_mov_b32_e32 v74, v2
	v_rcp_f32_e32 v2, v71
	v_mov_b32_e32 v75, v18
	v_mov_b32_e32 v18, v3
	v_pk_mul_f32 v[76:77], v[86:87], v[86:87]
	v_pk_mul_f32 v[80:81], v[34:35], v[2:3] op_sel_hi:[1,0]
	v_pk_mul_f32 v[84:85], v[74:75], v[70:71] op_sel_hi:[1,0]
	v_pk_mul_f32 v[34:35], v[80:81], v[80:81]
	v_pk_mul_f32 v[74:75], v[18:19], v[2:3] op_sel_hi:[1,0]
	v_pk_mul_f32 v[78:79], v[84:85], v[84:85]
	v_pk_mul_f32 v[2:3], v[74:75], v[74:75]
	v_mov_b32_e32 v18, v34
	v_mov_b32_e32 v19, v76
	v_mov_b32_e32 v76, v35
	v_pk_add_f32 v[18:19], v[18:19], v[76:77]
	v_mov_b32_e32 v34, v3
	v_mov_b32_e32 v35, v79
	v_pk_add_f32 v[18:19], v[34:35], v[18:19]
	v_mov_b32_e32 v3, v78
	v_pk_add_f32 v[2:3], v[2:3], v[18:19]
	s_nop 1
	v_mov_b32_dpp v19, v3 quad_perm:[1,0,3,2] row_mask:0xf bank_mask:0xf
	s_nop 1
	v_mov_b32_dpp v18, v2 quad_perm:[1,0,3,2] row_mask:0xf bank_mask:0xf
	v_mov_b32_e32 v34, v4
	v_rcp_f32_e32 v4, v73
	v_mov_b32_e32 v35, v20
	v_mov_b32_e32 v20, v5
	s_waitcnt lgkmcnt(0)
	v_pk_add_f32 v[2:3], v[2:3], v[18:19]
	ds_bpermute_b32 v19, v118, v3
	ds_bpermute_b32 v18, v118, v2
	s_waitcnt lgkmcnt(0)
	v_pk_add_f32 v[2:3], v[2:3], v[18:19]
	ds_bpermute_b32 v19, v119, v3
	ds_bpermute_b32 v18, v119, v2
	s_waitcnt lgkmcnt(0)
	v_pk_add_f32 v[2:3], v[2:3], v[18:19]
	ds_bpermute_b32 v19, v120, v3
	ds_bpermute_b32 v18, v120, v2
	s_waitcnt lgkmcnt(0)
	v_pk_add_f32 v[2:3], v[2:3], v[18:19]
	ds_bpermute_b32 v19, v121, v3
	ds_bpermute_b32 v18, v121, v2
	s_waitcnt lgkmcnt(0)
	v_pk_add_f32 v[2:3], v[2:3], v[18:19]
	s_nop 0
	v_pk_fma_f32 v[94:95], v[2:3], s[48:49], v[198:199] op_sel_hi:[1,0,0]
	v_mov_b32_e32 v18, v52
	v_mul_f32_e32 v2, 0x4b800000, v95
	v_cmp_gt_f32_e64 s[10:11], s44, v95
	v_mov_b32_e32 v19, v36
	v_mov_b32_e32 v36, v53
	v_cndmask_b32_e64 v2, v95, v2, s[10:11]
	v_rsq_f32_e32 v2, v2
	v_pk_mul_f32 v[78:79], v[36:37], v[4:5] op_sel_hi:[1,0]
	v_cmp_gt_f32_e32 vcc, s44, v94
	v_mul_f32_e32 v3, 0x45800000, v2
	v_cndmask_b32_e64 v117, v2, v3, s[10:11]
	v_rcp_f32_e32 v2, v72
	v_pk_mul_f32 v[72:73], v[20:21], v[4:5] op_sel_hi:[1,0]
	s_lshl_b64 s[10:11], s[72:73], 12
	v_pk_mul_f32 v[4:5], v[72:73], v[72:73]
	v_pk_mul_f32 v[88:89], v[18:19], v[2:3] op_sel_hi:[1,0]
	v_pk_mul_f32 v[82:83], v[34:35], v[2:3] op_sel_hi:[1,0]
	v_pk_mul_f32 v[18:19], v[88:89], v[88:89]
	v_pk_mul_f32 v[34:35], v[78:79], v[78:79]
	v_pk_mul_f32 v[2:3], v[82:83], v[82:83]
	v_mov_b32_e32 v20, v34
	v_mov_b32_e32 v21, v18
	v_mov_b32_e32 v18, v35
	v_pk_add_f32 v[18:19], v[20:21], v[18:19]
	v_mov_b32_e32 v20, v5
	v_mov_b32_e32 v21, v3
	v_pk_add_f32 v[18:19], v[20:21], v[18:19]
	v_mov_b32_e32 v5, v2
	v_pk_add_f32 v[2:3], v[4:5], v[18:19]
	s_nop 1
	v_mov_b32_dpp v5, v3 quad_perm:[1,0,3,2] row_mask:0xf bank_mask:0xf
	s_nop 1
	v_mov_b32_dpp v4, v2 quad_perm:[1,0,3,2] row_mask:0xf bank_mask:0xf
	v_mov_b32_e32 v18, v6
	v_rcp_f32_e32 v6, v67
	v_mov_b32_e32 v19, v22
	v_mov_b32_e32 v22, v7
	s_waitcnt lgkmcnt(0)
	v_pk_add_f32 v[2:3], v[2:3], v[4:5]
	ds_bpermute_b32 v5, v118, v3
	ds_bpermute_b32 v4, v118, v2
	v_pk_mul_f32 v[50:51], v[22:23], v[6:7] op_sel_hi:[1,0]
	s_add_u32 s12, s70, s10
	s_addc_u32 s13, s71, s11
	s_waitcnt lgkmcnt(0)
	v_pk_add_f32 v[2:3], v[2:3], v[4:5]
	ds_bpermute_b32 v5, v119, v3
	ds_bpermute_b32 v4, v119, v2
	s_waitcnt lgkmcnt(0)
	v_pk_add_f32 v[2:3], v[2:3], v[4:5]
	ds_bpermute_b32 v5, v120, v3
	ds_bpermute_b32 v4, v120, v2
	s_waitcnt lgkmcnt(0)
	v_pk_add_f32 v[96:97], v[2:3], v[4:5]
	v_rcp_f32_e32 v2, v66
	v_mov_b32_e32 v4, v54
	v_mov_b32_e32 v5, v38
	v_mov_b32_e32 v38, v55
	v_pk_mul_f32 v[76:77], v[4:5], v[2:3] op_sel_hi:[1,0]
	v_pk_mul_f32 v[54:55], v[38:39], v[6:7] op_sel_hi:[1,0]
	v_pk_mul_f32 v[4:5], v[76:77], v[76:77]
	v_pk_mul_f32 v[70:71], v[18:19], v[2:3] op_sel_hi:[1,0]
	v_pk_mul_f32 v[18:19], v[54:55], v[54:55]
	v_pk_mul_f32 v[2:3], v[70:71], v[70:71]
	v_pk_mul_f32 v[6:7], v[50:51], v[50:51]
	v_mov_b32_e32 v20, v18
	v_mov_b32_e32 v21, v4
	v_mov_b32_e32 v4, v19
	v_pk_add_f32 v[4:5], v[20:21], v[4:5]
	v_mov_b32_e32 v18, v7
	v_mov_b32_e32 v19, v3
	v_pk_add_f32 v[4:5], v[18:19], v[4:5]
	v_mov_b32_e32 v7, v2
	v_pk_add_f32 v[2:3], v[6:7], v[4:5]
	s_nop 1
	v_mov_b32_dpp v5, v3 quad_perm:[1,0,3,2] row_mask:0xf bank_mask:0xf
	s_nop 1
	v_mov_b32_dpp v4, v2 quad_perm:[1,0,3,2] row_mask:0xf bank_mask:0xf
	v_mov_b32_e32 v6, v8
	v_mov_b32_e32 v7, v24
	v_mov_b32_e32 v24, v9
	ds_bpermute_b32 v115, v121, v97
	s_waitcnt lgkmcnt(0)
; __device__ __forceinline__ int crow(int r, int hi) { return (r & 3) + 8 * (r >> 2) + 4 * hi; }
; __device__ __forceinline__ bool fox_block(const BlockRef& cur, BlockRef& nxt, unsigned* ctr, const unsigned* nrm, bf16_t* PROJ, bf16_t* MIX, char* lds, Seam& S, const float* __restrict__ CF, const float* __restrict__ fnorm) {
;     ...
;     for (int r = 0; r < 16; ++r) { const float rl = __builtin_amdgcn_rcpf(li_l[crow(r, hi)]); float a = 0.f;
; #pragma unroll
;         for (int d0 = 0; d0 < 4; ++d0) { const float v = o[d0][r] * rl; o[d0][r] = v; a += v * v; }
;         a += __shfl_xor(a, 1); a += __shfl_xor(a, 2); a += __shfl_xor(a, 4); a += __shfl_xor(a, 8); a += __shfl_xor(a, 16);
;         rs[r] = rsqrtf(a * (1.f / 128.f) + RMS_EPS); }
	v_pk_add_f32 v[2:3], v[2:3], v[4:5]
	ds_bpermute_b32 v5, v118, v3
	ds_bpermute_b32 v4, v118, v2
	ds_bpermute_b32 v114, v121, v96
	s_waitcnt lgkmcnt(0)
	v_pk_add_f32 v[2:3], v[2:3], v[4:5]
	ds_bpermute_b32 v5, v119, v3
	ds_bpermute_b32 v4, v119, v2
	s_waitcnt lgkmcnt(0)
	v_pk_add_f32 v[2:3], v[2:3], v[4:5]
	ds_bpermute_b32 v5, v120, v3
	ds_bpermute_b32 v4, v120, v2
	s_waitcnt lgkmcnt(0)
	v_pk_add_f32 v[90:91], v[2:3], v[4:5]
	v_rcp_f32_e32 v2, v68
	v_mov_b32_e32 v4, v56
	v_mov_b32_e32 v5, v40
	v_mov_b32_e32 v40, v57
	v_pk_mul_f32 v[52:53], v[6:7], v[2:3] op_sel_hi:[1,0]
	v_rcp_f32_e32 v6, v69
	v_pk_mul_f32 v[66:67], v[4:5], v[2:3] op_sel_hi:[1,0]
	v_pk_mul_f32 v[2:3], v[52:53], v[52:53]
	v_pk_mul_f32 v[4:5], v[66:67], v[66:67]
	v_pk_mul_f32 v[40:41], v[40:41], v[6:7] op_sel_hi:[1,0]
	v_pk_mul_f32 v[36:37], v[24:25], v[6:7] op_sel_hi:[1,0]
	v_pk_mul_f32 v[18:19], v[40:41], v[40:41]
	v_pk_mul_f32 v[6:7], v[36:37], v[36:37]
	v_mov_b32_e32 v8, v18
	v_mov_b32_e32 v9, v4
	v_mov_b32_e32 v4, v19
	v_pk_add_f32 v[4:5], v[8:9], v[4:5]
	v_mov_b32_e32 v8, v7
	v_mov_b32_e32 v9, v3
	v_pk_add_f32 v[4:5], v[8:9], v[4:5]
	v_mov_b32_e32 v7, v2
	v_pk_add_f32 v[2:3], v[6:7], v[4:5]
	s_nop 1
	v_mov_b32_dpp v5, v3 quad_perm:[1,0,3,2] row_mask:0xf bank_mask:0xf
	s_nop 1
	v_mov_b32_dpp v4, v2 quad_perm:[1,0,3,2] row_mask:0xf bank_mask:0xf
	v_mov_b32_e32 v6, v58
	v_mov_b32_e32 v7, v42
	v_mov_b32_e32 v8, v10
	v_mov_b32_e32 v9, v26
	s_waitcnt lgkmcnt(0)
	v_pk_add_f32 v[2:3], v[2:3], v[4:5]
	ds_bpermute_b32 v5, v118, v3
	ds_bpermute_b32 v4, v118, v2
	v_mov_b32_e32 v42, v59
	v_mov_b32_e32 v26, v11
	ds_bpermute_b32 v93, v121, v91
	ds_bpermute_b32 v92, v121, v90
	s_waitcnt lgkmcnt(0)
	v_pk_add_f32 v[2:3], v[2:3], v[4:5]
	ds_bpermute_b32 v5, v119, v3
	ds_bpermute_b32 v4, v119, v2
	s_waitcnt lgkmcnt(0)
	v_pk_add_f32 v[2:3], v[2:3], v[4:5]
	ds_bpermute_b32 v5, v120, v3
	ds_bpermute_b32 v4, v120, v2
	s_waitcnt lgkmcnt(0)
	v_pk_add_f32 v[56:57], v[2:3], v[4:5]
	ds_read_b128 v[2:5], v212 offset:64
	ds_bpermute_b32 v69, v121, v57
	ds_bpermute_b32 v68, v121, v56
	s_waitcnt lgkmcnt(0)
	v_rcp_f32_e32 v2, v2
	s_nop 0
	v_pk_mul_f32 v[38:39], v[6:7], v[2:3] op_sel_hi:[1,0]
	v_pk_mul_f32 v[34:35], v[8:9], v[2:3] op_sel_hi:[1,0]
	v_rcp_f32_e32 v2, v3
	v_pk_mul_f32 v[6:7], v[38:39], v[38:39]
	v_pk_mul_f32 v[8:9], v[34:35], v[34:35]
	v_mov_b32_e32 v11, v6
	v_pk_mul_f32 v[24:25], v[42:43], v[2:3] op_sel_hi:[1,0]
	v_pk_mul_f32 v[20:21], v[26:27], v[2:3] op_sel_hi:[1,0]
	v_pk_mul_f32 v[18:19], v[24:25], v[24:25]
	v_pk_mul_f32 v[2:3], v[20:21], v[20:21]
	v_mov_b32_e32 v10, v18
	v_mov_b32_e32 v6, v19
	v_pk_add_f32 v[6:7], v[10:11], v[6:7]
	v_mov_b32_e32 v10, v3
	v_mov_b32_e32 v11, v9
	v_pk_add_f32 v[6:7], v[10:11], v[6:7]
	v_mov_b32_e32 v3, v8
	v_pk_add_f32 v[2:3], v[2:3], v[6:7]
	s_nop 1
	v_mov_b32_dpp v7, v3 quad_perm:[1,0,3,2] row_mask:0xf bank_mask:0xf
	s_nop 1
	v_mov_b32_dpp v6, v2 quad_perm:[1,0,3,2] row_mask:0xf bank_mask:0xf
	s_waitcnt lgkmcnt(0)
	v_pk_add_f32 v[2:3], v[2:3], v[6:7]
	ds_bpermute_b32 v7, v118, v3
	ds_bpermute_b32 v6, v118, v2
	s_waitcnt lgkmcnt(0)
	v_pk_add_f32 v[2:3], v[2:3], v[6:7]
	ds_bpermute_b32 v7, v119, v3
	ds_bpermute_b32 v6, v119, v2
	s_waitcnt lgkmcnt(0)
	v_pk_add_f32 v[2:3], v[2:3], v[6:7]
	ds_bpermute_b32 v7, v120, v3
	ds_bpermute_b32 v6, v120, v2
	s_waitcnt lgkmcnt(0)
	v_pk_add_f32 v[26:27], v[2:3], v[6:7]
	v_rcp_f32_e32 v2, v4
	v_rcp_f32_e32 v4, v5
	v_mov_b32_e32 v6, v60
	v_mov_b32_e32 v7, v44
	v_mov_b32_e32 v44, v61
	v_pk_mul_f32 v[18:19], v[6:7], v[2:3] op_sel_hi:[1,0]
	v_mov_b32_e32 v6, v12
	v_mov_b32_e32 v7, v28
	v_pk_mul_f32 v[8:9], v[44:45], v[4:5] op_sel_hi:[1,0]
	v_mov_b32_e32 v28, v13
	v_pk_mul_f32 v[22:23], v[18:19], v[18:19]
	v_pk_mul_f32 v[10:11], v[6:7], v[2:3] op_sel_hi:[1,0]
	v_pk_mul_f32 v[44:45], v[8:9], v[8:9]
	v_pk_mul_f32 v[6:7], v[28:29], v[4:5] op_sel_hi:[1,0]
	v_pk_mul_f32 v[2:3], v[10:11], v[10:11]
	v_pk_mul_f32 v[4:5], v[6:7], v[6:7]
	v_mov_b32_e32 v12, v44
	v_mov_b32_e32 v13, v22
	v_mov_b32_e32 v22, v45
	v_pk_add_f32 v[12:13], v[12:13], v[22:23]
	v_mov_b32_e32 v22, v5
	v_mov_b32_e32 v23, v3
	v_pk_add_f32 v[12:13], v[22:23], v[12:13]
	v_mov_b32_e32 v5, v2
	v_pk_add_f32 v[2:3], v[4:5], v[12:13]
	s_nop 1
	v_mov_b32_dpp v5, v3 quad_perm:[1,0,3,2] row_mask:0xf bank_mask:0xf
	s_nop 1
	v_mov_b32_dpp v4, v2 quad_perm:[1,0,3,2] row_mask:0xf bank_mask:0xf
	v_mov_b32_e32 v28, v62
	v_mov_b32_e32 v29, v46
	v_mov_b32_e32 v44, v14
	v_mov_b32_e32 v45, v30
	s_waitcnt lgkmcnt(0)
	v_pk_add_f32 v[2:3], v[2:3], v[4:5]
	ds_bpermute_b32 v5, v118, v3
	ds_bpermute_b32 v4, v118, v2
	v_mov_b32_e32 v46, v63
	v_mov_b32_e32 v30, v15
	ds_bpermute_b32 v43, v121, v27
	ds_bpermute_b32 v42, v121, v26
	s_waitcnt lgkmcnt(0)
	v_pk_add_f32 v[2:3], v[2:3], v[4:5]
	ds_bpermute_b32 v5, v119, v3
	ds_bpermute_b32 v4, v119, v2
	s_waitcnt lgkmcnt(0)
	v_pk_add_f32 v[2:3], v[2:3], v[4:5]
	ds_bpermute_b32 v5, v120, v3
	ds_bpermute_b32 v4, v120, v2
	s_waitcnt lgkmcnt(0)
	v_pk_add_f32 v[12:13], v[2:3], v[4:5]
	ds_read_b128 v[2:5], v212 offset:96
	ds_bpermute_b32 v23, v121, v13
	ds_bpermute_b32 v22, v121, v12
	s_waitcnt lgkmcnt(0)
	v_rcp_f32_e32 v2, v2
	s_nop 0
	v_pk_mul_f32 v[60:61], v[28:29], v[2:3] op_sel_hi:[1,0]
	v_pk_mul_f32 v[58:59], v[44:45], v[2:3] op_sel_hi:[1,0]
	v_rcp_f32_e32 v2, v3
	v_pk_mul_f32 v[28:29], v[60:61], v[60:61]
	v_pk_mul_f32 v[122:123], v[58:59], v[58:59]
	v_mov_b32_e32 v15, v28
	v_pk_mul_f32 v[44:45], v[46:47], v[2:3] op_sel_hi:[1,0]
	v_pk_mul_f32 v[30:31], v[30:31], v[2:3] op_sel_hi:[1,0]
	v_pk_mul_f32 v[46:47], v[44:45], v[44:45]
	v_pk_mul_f32 v[2:3], v[30:31], v[30:31]
	v_mov_b32_e32 v14, v46
	v_mov_b32_e32 v28, v47
	v_pk_add_f32 v[14:15], v[14:15], v[28:29]
	v_mov_b32_e32 v28, v3
	v_mov_b32_e32 v29, v123
	v_pk_add_f32 v[14:15], v[28:29], v[14:15]
	v_mov_b32_e32 v3, v122
	v_pk_add_f32 v[2:3], v[2:3], v[14:15]
	s_nop 1
	v_mov_b32_dpp v15, v3 quad_perm:[1,0,3,2] row_mask:0xf bank_mask:0xf
	s_nop 1
	v_mov_b32_dpp v14, v2 quad_perm:[1,0,3,2] row_mask:0xf bank_mask:0xf
	s_waitcnt lgkmcnt(0)
; __device__ __forceinline__ unsigned cvt_pk_bf16(float lo, float hi) { unsigned r; asm volatile("v_cvt_pk_bf16_f32 %0, %1, %2" : "=v"(r) : "v"(lo), "v"(hi)); return r; }
; __device__ __forceinline__ int crow(int r, int hi) { return (r & 3) + 8 * (r >> 2) + 4 * hi; }
; __device__ __forceinline__ bool fox_block(const BlockRef& cur, BlockRef& nxt, unsigned* ctr, const unsigned* nrm, bf16_t* PROJ, bf16_t* MIX, char* lds, Seam& S, const float* __restrict__ CF, const float* __restrict__ fnorm) {
;     ...
;     for (int r = 0; r < 16; ++r) { const float rl = __builtin_amdgcn_rcpf(li_l[crow(r, hi)]); float a = 0.f;
; #pragma unroll
;         for (int d0 = 0; d0 < 4; ++d0) { const float v = o[d0][r] * rl; o[d0][r] = v; a += v * v; }
;         a += __shfl_xor(a, 1); a += __shfl_xor(a, 2); a += __shfl_xor(a, 4); a += __shfl_xor(a, 8); a += __shfl_xor(a, 16);
;         rs[r] = rsqrtf(a * (1.f / 128.f) + RMS_EPS); }
;     float gn[4];
; #pragma unroll
;     for (int d0 = 0; d0 < 4; ++d0) gn[d0] = fnorm[cur.head * 128 + d0 * 32 + r32];
;     bf16_t* Ow = cur.O + (size_t)(wid * QBLK) * DM;
; #pragma unroll
;     for (int r = 0; r < 16; ++r) { const int orow = crow(r, hi);
; #pragma unroll
;         for (int d0 = 0; d0 < 4; ++d0) { const float v = o[d0][r] * rs[r] * gn[d0];
;             const float vn = __shfl_xor(v, 1);
;             if ((r32 & 1) == 0) *(unsigned*)(Ow + (size_t)orow * DM + d0 * 32 + r32) = cvt_pk_bf16(v, vn); } }
	v_pk_add_f32 v[2:3], v[2:3], v[14:15]
	ds_bpermute_b32 v15, v118, v3
	ds_bpermute_b32 v14, v118, v2
	s_waitcnt lgkmcnt(0)
	v_pk_add_f32 v[2:3], v[2:3], v[14:15]
	ds_bpermute_b32 v15, v119, v3
	ds_bpermute_b32 v14, v119, v2
	s_waitcnt lgkmcnt(0)
	v_pk_add_f32 v[2:3], v[2:3], v[14:15]
	ds_bpermute_b32 v15, v120, v3
	ds_bpermute_b32 v14, v120, v2
	s_waitcnt lgkmcnt(0)
	v_pk_add_f32 v[46:47], v[2:3], v[14:15]
	v_rcp_f32_e32 v2, v4
	v_mov_b32_e32 v14, v64
	v_mov_b32_e32 v15, v48
	v_mov_b32_e32 v48, v65
	v_pk_mul_f32 v[28:29], v[14:15], v[2:3] op_sel_hi:[1,0]
	v_mov_b32_e32 v14, v16
	v_mov_b32_e32 v15, v32
	v_pk_mul_f32 v[14:15], v[14:15], v[2:3] op_sel_hi:[1,0]
	v_rcp_f32_e32 v2, v5
	v_mov_b32_e32 v32, v17
	v_pk_mul_f32 v[122:123], v[28:29], v[28:29]
	v_pk_mul_f32 v[124:125], v[14:15], v[14:15]
	v_pk_mul_f32 v[4:5], v[48:49], v[2:3] op_sel_hi:[1,0]
	v_pk_mul_f32 v[2:3], v[32:33], v[2:3] op_sel_hi:[1,0]
	v_pk_mul_f32 v[48:49], v[4:5], v[4:5]
	v_pk_mul_f32 v[16:17], v[2:3], v[2:3]
	v_mov_b32_e32 v32, v48
	v_mov_b32_e32 v33, v122
	v_mov_b32_e32 v122, v49
	v_pk_add_f32 v[32:33], v[32:33], v[122:123]
	v_mov_b32_e32 v48, v17
	v_mov_b32_e32 v49, v125
	v_pk_add_f32 v[32:33], v[48:49], v[32:33]
	v_mov_b32_e32 v17, v124
	v_pk_add_f32 v[16:17], v[16:17], v[32:33]
	s_nop 1
	v_mov_b32_dpp v33, v17 quad_perm:[1,0,3,2] row_mask:0xf bank_mask:0xf
	s_nop 1
	v_mov_b32_dpp v32, v16 quad_perm:[1,0,3,2] row_mask:0xf bank_mask:0xf
	v_lshl_add_u64 v[48:49], v[196:197], 2, s[18:19]
	v_mul_f32_e32 v64, v86, v117
	ds_bpermute_b32 v63, v121, v47
	ds_bpermute_b32 v62, v121, v46
	s_waitcnt lgkmcnt(0)
	v_pk_add_f32 v[16:17], v[16:17], v[32:33]
	ds_bpermute_b32 v33, v118, v17
	ds_bpermute_b32 v32, v118, v16
	v_lshlrev_b32_e32 v196, 1, v211
	s_waitcnt lgkmcnt(0)
	v_pk_add_f32 v[16:17], v[16:17], v[32:33]
	ds_bpermute_b32 v33, v119, v17
	ds_bpermute_b32 v32, v119, v16
	s_waitcnt lgkmcnt(0)
	v_pk_add_f32 v[16:17], v[16:17], v[32:33]
	ds_bpermute_b32 v33, v120, v17
	ds_bpermute_b32 v32, v120, v16
	flat_load_dword v120, v[48:49]
	flat_load_dword v119, v[48:49] offset:128
	flat_load_dword v118, v[48:49] offset:256
	flat_load_dword v95, v[48:49] offset:384
	v_and_b32_e32 v48, 1, v202
	v_cmp_eq_u32_e64 s[10:11], 0, v48
	v_lshl_add_u64 v[48:49], s[12:13], 0, v[196:197]
	s_waitcnt lgkmcnt(0)
	v_pk_add_f32 v[16:17], v[16:17], v[32:33]
	ds_bpermute_b32 v33, v121, v17
	ds_bpermute_b32 v32, v121, v16
	v_lshlrev_b32_e32 v196, 14, v203
	v_lshl_add_u64 v[48:49], v[48:49], 0, v[196:197]
	s_waitcnt vmcnt(0)
	v_mul_f32_e32 v64, v64, v120
	s_nop 1
	v_mov_b32_dpp v65, v64 quad_perm:[1,0,3,2] row_mask:0xf bank_mask:0xf
	s_and_saveexec_b64 s[12:13], s[10:11]
	s_cbranch_execz .LBB0_826
	s_waitcnt lgkmcnt(0)
	v_cvt_pk_bf16_f32 v64, v64, v65
	global_store_dword v[48:49], v64, off
.LBB0_826:
	s_or_b64 exec, exec, s[12:13]
	v_mul_f32_e32 v64, v87, v117
	v_mul_f32_e32 v64, v64, v119
	s_waitcnt lgkmcnt(0)
	s_nop 1
	v_mov_b32_dpp v65, v64 quad_perm:[1,0,3,2] row_mask:0xf bank_mask:0xf
	s_and_saveexec_b64 s[12:13], s[10:11]
	s_cbranch_execz .LBB0_828
	s_waitcnt lgkmcnt(0)
	v_cvt_pk_bf16_f32 v64, v64, v65
	global_store_dword v[48:49], v64, off offset:64
.LBB0_828:
	s_or_b64 exec, exec, s[12:13]
	v_mul_f32_e32 v64, v85, v117
	v_mul_f32_e32 v64, v64, v118
	s_waitcnt lgkmcnt(0)
	s_nop 1
	v_mov_b32_dpp v65, v64 quad_perm:[1,0,3,2] row_mask:0xf bank_mask:0xf
	s_and_saveexec_b64 s[12:13], s[10:11]
	s_cbranch_execz .LBB0_830
	s_waitcnt lgkmcnt(0)
	v_cvt_pk_bf16_f32 v64, v64, v65
	global_store_dword v[48:49], v64, off offset:128
.LBB0_830:
	s_or_b64 exec, exec, s[12:13]
	v_mul_f32_e32 v64, v84, v117
	v_mul_f32_e32 v64, v64, v95
	s_waitcnt lgkmcnt(0)
	s_nop 1
	v_mov_b32_dpp v65, v64 quad_perm:[1,0,3,2] row_mask:0xf bank_mask:0xf
	s_and_saveexec_b64 s[12:13], s[10:11]
	s_cbranch_execz .LBB0_832
	s_waitcnt lgkmcnt(0)
	v_cvt_pk_bf16_f32 v64, v64, v65
	global_store_dword v[48:49], v64, off offset:192
.LBB0_832:
	s_or_b64 exec, exec, s[12:13]
	v_mul_f32_e32 v64, 0x4b800000, v94
	v_cndmask_b32_e32 v64, v94, v64, vcc
	v_rsq_f32_e32 v64, v64
	s_waitcnt lgkmcnt(0)
	v_mul_f32_e32 v65, 0x45800000, v64
	v_cndmask_b32_e32 v64, v64, v65, vcc
	v_mul_f32_e32 v65, v80, v64
	v_mul_f32_e32 v65, v65, v120
	s_nop 1
	v_mov_b32_dpp v80, v65 quad_perm:[1,0,3,2] row_mask:0xf bank_mask:0xf
	s_and_saveexec_b64 s[12:13], s[10:11]
	s_cbranch_execz .LBB0_834
	v_add_co_u32_e32 v84, vcc, 0x1000, v48
	s_waitcnt lgkmcnt(0)
	v_cvt_pk_bf16_f32 v65, v65, v80
	s_nop 0
	v_addc_co_u32_e32 v85, vcc, 0, v49, vcc
	global_store_dword v[84:85], v65, off
.LBB0_834:
	s_or_b64 exec, exec, s[12:13]
	v_mul_f32_e32 v65, v81, v64
	v_mul_f32_e32 v65, v65, v119
	s_waitcnt lgkmcnt(0)
	s_nop 1
	v_mov_b32_dpp v80, v65 quad_perm:[1,0,3,2] row_mask:0xf bank_mask:0xf
	s_and_saveexec_b64 s[12:13], s[10:11]
	s_cbranch_execz .LBB0_836
	s_waitcnt lgkmcnt(0)
	v_cvt_pk_bf16_f32 v65, v65, v80
	v_add_co_u32_e32 v80, vcc, 0x1000, v48
	s_nop 1
	v_addc_co_u32_e32 v81, vcc, 0, v49, vcc
	global_store_dword v[80:81], v65, off offset:64
.LBB0_836:
	s_or_b64 exec, exec, s[12:13]
	v_mul_f32_e32 v65, v75, v64
	v_mul_f32_e32 v65, v65, v118
	s_nop 1
	v_mov_b32_dpp v75, v65 quad_perm:[1,0,3,2] row_mask:0xf bank_mask:0xf
	s_and_saveexec_b64 s[12:13], s[10:11]
	s_cbranch_execz .LBB0_838
	s_waitcnt lgkmcnt(0)
	v_add_co_u32_e32 v80, vcc, 0x1000, v48
	v_cvt_pk_bf16_f32 v65, v65, v75
	s_nop 1
	v_addc_co_u32_e32 v81, vcc, 0, v49, vcc
	global_store_dword v[80:81], v65, off offset:128
; __device__ __forceinline__ unsigned cvt_pk_bf16(float lo, float hi) { unsigned r; asm volatile("v_cvt_pk_bf16_f32 %0, %1, %2" : "=v"(r) : "v"(lo), "v"(hi)); return r; }
; __device__ __forceinline__ int crow(int r, int hi) { return (r & 3) + 8 * (r >> 2) + 4 * hi; }
; __device__ __forceinline__ bool fox_block(const BlockRef& cur, BlockRef& nxt, unsigned* ctr, const unsigned* nrm, bf16_t* PROJ, bf16_t* MIX, char* lds, Seam& S, const float* __restrict__ CF, const float* __restrict__ fnorm) {
;     ...
;         rs[r] = rsqrtf(a * (1.f / 128.f) + RMS_EPS); }
;     ...
;     for (int r = 0; r < 16; ++r) { const int orow = crow(r, hi);
; #pragma unroll
;         for (int d0 = 0; d0 < 4; ++d0) { const float v = o[d0][r] * rs[r] * gn[d0];
;             const float vn = __shfl_xor(v, 1);
;             if ((r32 & 1) == 0) *(unsigned*)(Ow + (size_t)orow * DM + d0 * 32 + r32) = cvt_pk_bf16(v, vn); } }
.LBB0_838:
	s_or_b64 exec, exec, s[12:13]
	v_mul_f32_e32 v64, v74, v64
	v_mul_f32_e32 v64, v64, v95
	s_nop 1
	v_mov_b32_dpp v65, v64 quad_perm:[1,0,3,2] row_mask:0xf bank_mask:0xf
	s_and_saveexec_b64 s[12:13], s[10:11]
	s_cbranch_execz .LBB0_840
	s_waitcnt lgkmcnt(0)
	v_cvt_pk_bf16_f32 v74, v64, v65
	v_add_co_u32_e32 v64, vcc, 0x1000, v48
	s_nop 1
	v_addc_co_u32_e32 v65, vcc, 0, v49, vcc
	global_store_dword v[64:65], v74, off offset:192
.LBB0_840:
	s_or_b64 exec, exec, s[12:13]
	s_waitcnt lgkmcnt(0)
	v_pk_add_f32 v[64:65], v[96:97], v[114:115]
	s_nop 0
	v_pk_fma_f32 v[64:65], v[64:65], s[48:49], v[198:199] op_sel_hi:[1,0,0]
	s_nop 0
	v_mul_f32_e32 v74, 0x4b800000, v65
	v_cmp_gt_f32_e32 vcc, s44, v65
	v_cmp_gt_f32_e64 s[12:13], s44, v64
	s_nop 0
	v_cndmask_b32_e32 v65, v65, v74, vcc
	v_rsq_f32_e32 v65, v65
	s_nop 0
	v_mul_f32_e32 v74, 0x45800000, v65
	v_cndmask_b32_e32 v65, v65, v74, vcc
	v_mul_f32_e32 v74, v88, v65
	v_mul_f32_e32 v74, v74, v120
	s_nop 1
	v_mov_b32_dpp v75, v74 quad_perm:[1,0,3,2] row_mask:0xf bank_mask:0xf
	s_and_saveexec_b64 s[72:73], s[10:11]
	s_cbranch_execz .LBB0_842
	s_waitcnt lgkmcnt(0)
	v_cvt_pk_bf16_f32 v80, v74, v75
	v_add_co_u32_e32 v74, vcc, 0x2000, v48
	s_nop 1
	v_addc_co_u32_e32 v75, vcc, 0, v49, vcc
	global_store_dword v[74:75], v80, off
.LBB0_842:
	s_or_b64 exec, exec, s[72:73]
	v_mul_f32_e32 v74, v89, v65
	v_mul_f32_e32 v74, v74, v119
	s_waitcnt lgkmcnt(0)
	s_nop 1
	v_mov_b32_dpp v75, v74 quad_perm:[1,0,3,2] row_mask:0xf bank_mask:0xf
	s_and_saveexec_b64 s[72:73], s[10:11]
	s_cbranch_execz .LBB0_844
	s_waitcnt lgkmcnt(0)
	v_cvt_pk_bf16_f32 v80, v74, v75
	v_add_co_u32_e32 v74, vcc, 0x2000, v48
	s_nop 1
	v_addc_co_u32_e32 v75, vcc, 0, v49, vcc
	global_store_dword v[74:75], v80, off offset:64
.LBB0_844:
	s_or_b64 exec, exec, s[72:73]
	v_mul_f32_e32 v74, v83, v65
	v_mul_f32_e32 v74, v74, v118
	s_waitcnt lgkmcnt(0)
	s_nop 1
	v_mov_b32_dpp v75, v74 quad_perm:[1,0,3,2] row_mask:0xf bank_mask:0xf
	s_and_saveexec_b64 s[72:73], s[10:11]
	s_cbranch_execz .LBB0_846
	s_waitcnt lgkmcnt(0)
	v_cvt_pk_bf16_f32 v80, v74, v75
	v_add_co_u32_e32 v74, vcc, 0x2000, v48
	s_nop 1
	v_addc_co_u32_e32 v75, vcc, 0, v49, vcc
	global_store_dword v[74:75], v80, off offset:128
.LBB0_846:
	s_or_b64 exec, exec, s[72:73]
	v_mul_f32_e32 v65, v82, v65
	v_mul_f32_e32 v65, v65, v95
	s_nop 1
	v_mov_b32_dpp v74, v65 quad_perm:[1,0,3,2] row_mask:0xf bank_mask:0xf
	s_and_saveexec_b64 s[72:73], s[10:11]
	s_cbranch_execz .LBB0_848
	s_waitcnt lgkmcnt(0)
	v_cvt_pk_bf16_f32 v65, v65, v74
	v_add_co_u32_e32 v74, vcc, 0x2000, v48
	s_nop 1
	v_addc_co_u32_e32 v75, vcc, 0, v49, vcc
	global_store_dword v[74:75], v65, off offset:192
.LBB0_848:
	s_or_b64 exec, exec, s[72:73]
	v_mul_f32_e32 v65, 0x4b800000, v64
	v_cndmask_b32_e64 v64, v64, v65, s[12:13]
	v_rsq_f32_e32 v64, v64
	s_nop 0
	v_mul_f32_e32 v65, 0x45800000, v64
	v_cndmask_b32_e64 v64, v64, v65, s[12:13]
	v_mul_f32_e32 v65, v78, v64
	v_mul_f32_e32 v65, v65, v120
	s_waitcnt lgkmcnt(0)
	s_nop 1
	v_mov_b32_dpp v74, v65 quad_perm:[1,0,3,2] row_mask:0xf bank_mask:0xf
	s_and_saveexec_b64 s[12:13], s[10:11]
	s_cbranch_execz .LBB0_850
	s_waitcnt lgkmcnt(0)
	v_cvt_pk_bf16_f32 v65, v65, v74
	v_add_co_u32_e32 v74, vcc, 0x3000, v48
	s_nop 1
	v_addc_co_u32_e32 v75, vcc, 0, v49, vcc
	global_store_dword v[74:75], v65, off
.LBB0_850:
	s_or_b64 exec, exec, s[12:13]
	v_mul_f32_e32 v65, v79, v64
	v_mul_f32_e32 v65, v65, v119
	s_waitcnt lgkmcnt(0)
	s_nop 1
	v_mov_b32_dpp v74, v65 quad_perm:[1,0,3,2] row_mask:0xf bank_mask:0xf
	s_and_saveexec_b64 s[12:13], s[10:11]
	s_cbranch_execz .LBB0_852
	s_waitcnt lgkmcnt(0)
	v_cvt_pk_bf16_f32 v65, v65, v74
	v_add_co_u32_e32 v74, vcc, 0x3000, v48
	s_nop 1
	v_addc_co_u32_e32 v75, vcc, 0, v49, vcc
	global_store_dword v[74:75], v65, off offset:64
.LBB0_852:
	s_or_b64 exec, exec, s[12:13]
	v_mul_f32_e32 v65, v73, v64
	v_mul_f32_e32 v65, v65, v118
	s_nop 1
	v_mov_b32_dpp v73, v65 quad_perm:[1,0,3,2] row_mask:0xf bank_mask:0xf
	s_and_saveexec_b64 s[12:13], s[10:11]
	s_cbranch_execz .LBB0_854
	s_waitcnt lgkmcnt(0)
	v_add_co_u32_e32 v74, vcc, 0x3000, v48
	v_cvt_pk_bf16_f32 v65, v65, v73
	s_nop 1
	v_addc_co_u32_e32 v75, vcc, 0, v49, vcc
	global_store_dword v[74:75], v65, off offset:128
.LBB0_854:
	s_or_b64 exec, exec, s[12:13]
	v_mul_f32_e32 v64, v72, v64
	v_mul_f32_e32 v64, v64, v95
	s_nop 1
	v_mov_b32_dpp v65, v64 quad_perm:[1,0,3,2] row_mask:0xf bank_mask:0xf
	s_and_saveexec_b64 s[12:13], s[10:11]
	s_cbranch_execz .LBB0_856
	s_waitcnt lgkmcnt(0)
	v_cvt_pk_bf16_f32 v72, v64, v65
	v_add_co_u32_e32 v64, vcc, 0x3000, v48
	s_nop 1
	v_addc_co_u32_e32 v65, vcc, 0, v49, vcc
	global_store_dword v[64:65], v72, off offset:192
.LBB0_856:
	s_or_b64 exec, exec, s[12:13]
	s_waitcnt lgkmcnt(0)
	v_pk_add_f32 v[64:65], v[90:91], v[92:93]
	s_nop 0
	v_pk_fma_f32 v[64:65], v[64:65], s[48:49], v[198:199] op_sel_hi:[1,0,0]
	s_nop 0
	v_mul_f32_e32 v72, 0x4b800000, v65
	v_cmp_gt_f32_e32 vcc, s44, v65
	v_cmp_gt_f32_e64 s[12:13], s44, v64
	s_nop 0
	v_cndmask_b32_e32 v65, v65, v72, vcc
	v_rsq_f32_e32 v65, v65
	s_nop 0
	v_mul_f32_e32 v72, 0x45800000, v65
	v_cndmask_b32_e32 v65, v65, v72, vcc
	v_mul_f32_e32 v72, v76, v65
	v_mul_f32_e32 v72, v72, v120
	s_nop 1
	v_mov_b32_dpp v73, v72 quad_perm:[1,0,3,2] row_mask:0xf bank_mask:0xf
	s_and_saveexec_b64 s[72:73], s[10:11]
	s_cbranch_execz .LBB0_858
	s_waitcnt lgkmcnt(0)
	v_cvt_pk_bf16_f32 v74, v72, v73
	v_add_co_u32_e32 v72, vcc, 0x8000, v48
	s_nop 1
	v_addc_co_u32_e32 v73, vcc, 0, v49, vcc
	global_store_dword v[72:73], v74, off
; __device__ __forceinline__ unsigned cvt_pk_bf16(float lo, float hi) { unsigned r; asm volatile("v_cvt_pk_bf16_f32 %0, %1, %2" : "=v"(r) : "v"(lo), "v"(hi)); return r; }
; __device__ __forceinline__ int crow(int r, int hi) { return (r & 3) + 8 * (r >> 2) + 4 * hi; }
; __device__ __forceinline__ bool fox_block(const BlockRef& cur, BlockRef& nxt, unsigned* ctr, const unsigned* nrm, bf16_t* PROJ, bf16_t* MIX, char* lds, Seam& S, const float* __restrict__ CF, const float* __restrict__ fnorm) {
;     ...
;         rs[r] = rsqrtf(a * (1.f / 128.f) + RMS_EPS); }
;     ...
;     for (int r = 0; r < 16; ++r) { const int orow = crow(r, hi);
; #pragma unroll
;         for (int d0 = 0; d0 < 4; ++d0) { const float v = o[d0][r] * rs[r] * gn[d0];
;             const float vn = __shfl_xor(v, 1);
;             if ((r32 & 1) == 0) *(unsigned*)(Ow + (size_t)orow * DM + d0 * 32 + r32) = cvt_pk_bf16(v, vn); } }
.LBB0_858:
	s_or_b64 exec, exec, s[72:73]
	v_mul_f32_e32 v72, v77, v65
	v_mul_f32_e32 v72, v72, v119
	s_waitcnt lgkmcnt(0)
	s_nop 1
	v_mov_b32_dpp v73, v72 quad_perm:[1,0,3,2] row_mask:0xf bank_mask:0xf
	s_and_saveexec_b64 s[72:73], s[10:11]
	s_cbranch_execz .LBB0_860
	s_waitcnt lgkmcnt(0)
	v_cvt_pk_bf16_f32 v74, v72, v73
	v_add_co_u32_e32 v72, vcc, 0x8000, v48
	s_nop 1
	v_addc_co_u32_e32 v73, vcc, 0, v49, vcc
	global_store_dword v[72:73], v74, off offset:64
.LBB0_860:
	s_or_b64 exec, exec, s[72:73]
	v_mul_f32_e32 v71, v71, v65
	v_mul_f32_e32 v71, v71, v118
	s_nop 1
	v_mov_b32_dpp v72, v71 quad_perm:[1,0,3,2] row_mask:0xf bank_mask:0xf
	s_and_saveexec_b64 s[72:73], s[10:11]
	s_cbranch_execz .LBB0_862
	s_waitcnt lgkmcnt(0)
	v_cvt_pk_bf16_f32 v71, v71, v72
	v_add_co_u32_e32 v72, vcc, 0x8000, v48
	s_nop 1
	v_addc_co_u32_e32 v73, vcc, 0, v49, vcc
	global_store_dword v[72:73], v71, off offset:128
.LBB0_862:
	s_or_b64 exec, exec, s[72:73]
	v_mul_f32_e32 v65, v70, v65
	v_mul_f32_e32 v65, v65, v95
	s_nop 1
	v_mov_b32_dpp v70, v65 quad_perm:[1,0,3,2] row_mask:0xf bank_mask:0xf
	s_and_saveexec_b64 s[72:73], s[10:11]
	s_cbranch_execz .LBB0_864
	s_waitcnt lgkmcnt(0)
	v_cvt_pk_bf16_f32 v65, v65, v70
	v_add_co_u32_e32 v70, vcc, 0x8000, v48
	s_nop 1
	v_addc_co_u32_e32 v71, vcc, 0, v49, vcc
	global_store_dword v[70:71], v65, off offset:192
.LBB0_864:
	s_or_b64 exec, exec, s[72:73]
	v_mul_f32_e32 v65, 0x4b800000, v64
	v_cndmask_b32_e64 v64, v64, v65, s[12:13]
	v_rsq_f32_e32 v64, v64
	s_nop 0
	v_mul_f32_e32 v65, 0x45800000, v64
	v_cndmask_b32_e64 v64, v64, v65, s[12:13]
	v_mul_f32_e32 v54, v54, v64
	v_mul_f32_e32 v54, v54, v120
	s_nop 1
	v_mov_b32_dpp v65, v54 quad_perm:[1,0,3,2] row_mask:0xf bank_mask:0xf
	s_and_saveexec_b64 s[12:13], s[10:11]
	s_cbranch_execz .LBB0_866
	s_waitcnt lgkmcnt(0)
	v_add_co_u32_e32 v70, vcc, 0x9000, v48
	v_cvt_pk_bf16_f32 v54, v54, v65
	s_nop 1
	v_addc_co_u32_e32 v71, vcc, 0, v49, vcc
	global_store_dword v[70:71], v54, off
.LBB0_866:
	s_or_b64 exec, exec, s[12:13]
	v_mul_f32_e32 v54, v55, v64
	v_mul_f32_e32 v54, v54, v119
	s_nop 1
	v_mov_b32_dpp v55, v54 quad_perm:[1,0,3,2] row_mask:0xf bank_mask:0xf
	s_and_saveexec_b64 s[12:13], s[10:11]
	s_cbranch_execz .LBB0_868
	s_waitcnt lgkmcnt(0)
	v_cvt_pk_bf16_f32 v65, v54, v55
	v_add_co_u32_e32 v54, vcc, 0x9000, v48
	s_nop 1
	v_addc_co_u32_e32 v55, vcc, 0, v49, vcc
	global_store_dword v[54:55], v65, off offset:64
.LBB0_868:
	s_or_b64 exec, exec, s[12:13]
	v_mul_f32_e32 v51, v51, v64
	v_mul_f32_e32 v51, v51, v118
	s_nop 1
	v_mov_b32_dpp v54, v51 quad_perm:[1,0,3,2] row_mask:0xf bank_mask:0xf
	s_and_saveexec_b64 s[12:13], s[10:11]
	s_cbranch_execz .LBB0_870
	s_waitcnt lgkmcnt(0)
	v_cvt_pk_bf16_f32 v51, v51, v54
	v_add_co_u32_e32 v54, vcc, 0x9000, v48
	s_nop 1
	v_addc_co_u32_e32 v55, vcc, 0, v49, vcc
	global_store_dword v[54:55], v51, off offset:128
.LBB0_870:
	s_or_b64 exec, exec, s[12:13]
	v_mul_f32_e32 v50, v50, v64
	v_mul_f32_e32 v50, v50, v95
	s_nop 1
	v_mov_b32_dpp v51, v50 quad_perm:[1,0,3,2] row_mask:0xf bank_mask:0xf
	s_and_saveexec_b64 s[12:13], s[10:11]
	s_cbranch_execz .LBB0_872
	s_waitcnt lgkmcnt(0)
	v_cvt_pk_bf16_f32 v54, v50, v51
	v_add_co_u32_e32 v50, vcc, 0x9000, v48
	s_nop 1
	v_addc_co_u32_e32 v51, vcc, 0, v49, vcc
	global_store_dword v[50:51], v54, off offset:192
.LBB0_872:
	s_or_b64 exec, exec, s[12:13]
	s_waitcnt lgkmcnt(0)
	v_pk_add_f32 v[50:51], v[56:57], v[68:69]
	s_nop 0
	v_pk_fma_f32 v[50:51], v[50:51], s[48:49], v[198:199] op_sel_hi:[1,0,0]
	s_nop 0
	v_mul_f32_e32 v54, 0x4b800000, v51
	v_cmp_gt_f32_e32 vcc, s44, v51
	v_cmp_gt_f32_e64 s[12:13], s44, v50
	s_nop 0
	v_cndmask_b32_e32 v51, v51, v54, vcc
	v_rsq_f32_e32 v51, v51
	s_nop 0
	v_mul_f32_e32 v54, 0x45800000, v51
	v_cndmask_b32_e32 v51, v51, v54, vcc
	v_mul_f32_e32 v54, v66, v51
	v_mul_f32_e32 v54, v54, v120
	s_nop 1
	v_mov_b32_dpp v55, v54 quad_perm:[1,0,3,2] row_mask:0xf bank_mask:0xf
	s_and_saveexec_b64 s[72:73], s[10:11]
	s_cbranch_execz .LBB0_874
	s_waitcnt lgkmcnt(0)
	v_cvt_pk_bf16_f32 v56, v54, v55
	v_add_co_u32_e32 v54, vcc, 0xa000, v48
	s_nop 1
	v_addc_co_u32_e32 v55, vcc, 0, v49, vcc
	global_store_dword v[54:55], v56, off
.LBB0_874:
	s_or_b64 exec, exec, s[72:73]
	v_mul_f32_e32 v54, v67, v51
	v_mul_f32_e32 v54, v54, v119
	s_waitcnt lgkmcnt(0)
	s_nop 1
	v_mov_b32_dpp v55, v54 quad_perm:[1,0,3,2] row_mask:0xf bank_mask:0xf
	s_and_saveexec_b64 s[72:73], s[10:11]
	s_cbranch_execz .LBB0_876
	s_waitcnt lgkmcnt(0)
	v_cvt_pk_bf16_f32 v56, v54, v55
	v_add_co_u32_e32 v54, vcc, 0xa000, v48
	s_nop 1
	v_addc_co_u32_e32 v55, vcc, 0, v49, vcc
	global_store_dword v[54:55], v56, off offset:64
.LBB0_876:
	s_or_b64 exec, exec, s[72:73]
	v_mul_f32_e32 v53, v53, v51
	v_mul_f32_e32 v53, v53, v118
	s_nop 1
	v_mov_b32_dpp v54, v53 quad_perm:[1,0,3,2] row_mask:0xf bank_mask:0xf
	s_and_saveexec_b64 s[72:73], s[10:11]
	s_cbranch_execz .LBB0_878
	s_waitcnt lgkmcnt(0)
	v_cvt_pk_bf16_f32 v53, v53, v54
	v_add_co_u32_e32 v54, vcc, 0xa000, v48
	s_nop 1
	v_addc_co_u32_e32 v55, vcc, 0, v49, vcc
	global_store_dword v[54:55], v53, off offset:128
.LBB0_878:
	s_or_b64 exec, exec, s[72:73]
	v_mul_f32_e32 v51, v52, v51
	v_mul_f32_e32 v51, v51, v95
	s_nop 1
	v_mov_b32_dpp v52, v51 quad_perm:[1,0,3,2] row_mask:0xf bank_mask:0xf
	s_and_saveexec_b64 s[72:73], s[10:11]
	s_cbranch_execz .LBB0_880
	s_waitcnt lgkmcnt(0)
	v_cvt_pk_bf16_f32 v51, v51, v52
	v_add_co_u32_e32 v52, vcc, 0xa000, v48
	s_nop 1
	v_addc_co_u32_e32 v53, vcc, 0, v49, vcc
	global_store_dword v[52:53], v51, off offset:192
; __device__ __forceinline__ unsigned cvt_pk_bf16(float lo, float hi) { unsigned r; asm volatile("v_cvt_pk_bf16_f32 %0, %1, %2" : "=v"(r) : "v"(lo), "v"(hi)); return r; }
; __device__ __forceinline__ int crow(int r, int hi) { return (r & 3) + 8 * (r >> 2) + 4 * hi; }
; __device__ __forceinline__ bool fox_block(const BlockRef& cur, BlockRef& nxt, unsigned* ctr, const unsigned* nrm, bf16_t* PROJ, bf16_t* MIX, char* lds, Seam& S, const float* __restrict__ CF, const float* __restrict__ fnorm) {
;     ...
;         rs[r] = rsqrtf(a * (1.f / 128.f) + RMS_EPS); }
;     ...
;     for (int r = 0; r < 16; ++r) { const int orow = crow(r, hi);
; #pragma unroll
;         for (int d0 = 0; d0 < 4; ++d0) { const float v = o[d0][r] * rs[r] * gn[d0];
;             const float vn = __shfl_xor(v, 1);
;             if ((r32 & 1) == 0) *(unsigned*)(Ow + (size_t)orow * DM + d0 * 32 + r32) = cvt_pk_bf16(v, vn); } }
.LBB0_880:
	s_or_b64 exec, exec, s[72:73]
	v_mul_f32_e32 v51, 0x4b800000, v50
	v_cndmask_b32_e64 v50, v50, v51, s[12:13]
	v_rsq_f32_e32 v50, v50
	s_nop 0
	v_mul_f32_e32 v51, 0x45800000, v50
	v_cndmask_b32_e64 v50, v50, v51, s[12:13]
	v_mul_f32_e32 v40, v40, v50
	v_mul_f32_e32 v40, v40, v120
	s_nop 1
	v_mov_b32_dpp v51, v40 quad_perm:[1,0,3,2] row_mask:0xf bank_mask:0xf
	s_and_saveexec_b64 s[12:13], s[10:11]
	s_cbranch_execz .LBB0_882
	s_waitcnt lgkmcnt(0)
	v_add_co_u32_e32 v52, vcc, 0xb000, v48
	v_cvt_pk_bf16_f32 v40, v40, v51
	s_nop 1
	v_addc_co_u32_e32 v53, vcc, 0, v49, vcc
	global_store_dword v[52:53], v40, off
.LBB0_882:
	s_or_b64 exec, exec, s[12:13]
	v_mul_f32_e32 v40, v41, v50
	v_mul_f32_e32 v40, v40, v119
	s_nop 1
	v_mov_b32_dpp v41, v40 quad_perm:[1,0,3,2] row_mask:0xf bank_mask:0xf
	s_and_saveexec_b64 s[12:13], s[10:11]
	s_cbranch_execz .LBB0_884
	s_waitcnt lgkmcnt(0)
	v_cvt_pk_bf16_f32 v51, v40, v41
	v_add_co_u32_e32 v40, vcc, 0xb000, v48
	s_nop 1
	v_addc_co_u32_e32 v41, vcc, 0, v49, vcc
	global_store_dword v[40:41], v51, off offset:64
.LBB0_884:
	s_or_b64 exec, exec, s[12:13]
	v_mul_f32_e32 v37, v37, v50
	v_mul_f32_e32 v37, v37, v118
	s_nop 1
	v_mov_b32_dpp v40, v37 quad_perm:[1,0,3,2] row_mask:0xf bank_mask:0xf
	s_and_saveexec_b64 s[12:13], s[10:11]
	s_cbranch_execz .LBB0_886
	s_waitcnt lgkmcnt(0)
	v_cvt_pk_bf16_f32 v37, v37, v40
	v_add_co_u32_e32 v40, vcc, 0xb000, v48
	s_nop 1
	v_addc_co_u32_e32 v41, vcc, 0, v49, vcc
	global_store_dword v[40:41], v37, off offset:128
.LBB0_886:
	s_or_b64 exec, exec, s[12:13]
	v_mul_f32_e32 v36, v36, v50
	v_mul_f32_e32 v36, v36, v95
	s_nop 1
	v_mov_b32_dpp v37, v36 quad_perm:[1,0,3,2] row_mask:0xf bank_mask:0xf
	s_and_saveexec_b64 s[12:13], s[10:11]
	s_cbranch_execz .LBB0_888
	s_waitcnt lgkmcnt(0)
	v_cvt_pk_bf16_f32 v40, v36, v37
	v_add_co_u32_e32 v36, vcc, 0xb000, v48
	s_nop 1
	v_addc_co_u32_e32 v37, vcc, 0, v49, vcc
	global_store_dword v[36:37], v40, off offset:192
.LBB0_888:
	s_or_b64 exec, exec, s[12:13]
	v_pk_add_f32 v[26:27], v[26:27], v[42:43]
	s_nop 0
	v_pk_fma_f32 v[26:27], v[26:27], s[48:49], v[198:199] op_sel_hi:[1,0,0]
	s_nop 0
	v_mul_f32_e32 v36, 0x4b800000, v27
	v_cmp_gt_f32_e32 vcc, s44, v27
	v_cmp_gt_f32_e64 s[12:13], s44, v26
	s_nop 0
	v_cndmask_b32_e32 v27, v27, v36, vcc
	v_rsq_f32_e32 v27, v27
	s_nop 0
	v_mul_f32_e32 v36, 0x45800000, v27
	v_cndmask_b32_e32 v27, v27, v36, vcc
	v_mul_f32_e32 v36, v38, v27
	v_mul_f32_e32 v36, v36, v120
	s_waitcnt lgkmcnt(0)
	s_nop 1
	v_mov_b32_dpp v37, v36 quad_perm:[1,0,3,2] row_mask:0xf bank_mask:0xf
	s_and_saveexec_b64 s[72:73], s[10:11]
	s_cbranch_execz .LBB0_890
	s_waitcnt lgkmcnt(0)
	v_cvt_pk_bf16_f32 v38, v36, v37
	v_add_co_u32_e32 v36, vcc, 0x10000, v48
	s_nop 1
	v_addc_co_u32_e32 v37, vcc, 0, v49, vcc
	global_store_dword v[36:37], v38, off
.LBB0_890:
	s_or_b64 exec, exec, s[72:73]
	v_mul_f32_e32 v36, v39, v27
	v_mul_f32_e32 v36, v36, v119
	s_waitcnt lgkmcnt(0)
	s_nop 1
	v_mov_b32_dpp v37, v36 quad_perm:[1,0,3,2] row_mask:0xf bank_mask:0xf
	s_and_saveexec_b64 s[72:73], s[10:11]
	s_cbranch_execz .LBB0_892
	s_waitcnt lgkmcnt(0)
	v_cvt_pk_bf16_f32 v38, v36, v37
	v_add_co_u32_e32 v36, vcc, 0x10000, v48
	s_nop 1
	v_addc_co_u32_e32 v37, vcc, 0, v49, vcc
	global_store_dword v[36:37], v38, off offset:64
.LBB0_892:
	s_or_b64 exec, exec, s[72:73]
	v_mul_f32_e32 v35, v35, v27
	v_mul_f32_e32 v35, v35, v118
	s_nop 1
	v_mov_b32_dpp v36, v35 quad_perm:[1,0,3,2] row_mask:0xf bank_mask:0xf
	s_and_saveexec_b64 s[72:73], s[10:11]
	s_cbranch_execz .LBB0_894
	s_waitcnt lgkmcnt(0)
	v_cvt_pk_bf16_f32 v35, v35, v36
	v_add_co_u32_e32 v36, vcc, 0x10000, v48
	s_nop 1
	v_addc_co_u32_e32 v37, vcc, 0, v49, vcc
	global_store_dword v[36:37], v35, off offset:128
.LBB0_894:
	s_or_b64 exec, exec, s[72:73]
	v_mul_f32_e32 v27, v34, v27
	v_mul_f32_e32 v27, v27, v95
	s_nop 1
	v_mov_b32_dpp v34, v27 quad_perm:[1,0,3,2] row_mask:0xf bank_mask:0xf
	s_and_saveexec_b64 s[72:73], s[10:11]
	s_cbranch_execz .LBB0_896
	s_waitcnt lgkmcnt(0)
	v_cvt_pk_bf16_f32 v27, v27, v34
	v_add_co_u32_e32 v34, vcc, 0x10000, v48
	s_nop 1
	v_addc_co_u32_e32 v35, vcc, 0, v49, vcc
	global_store_dword v[34:35], v27, off offset:192
.LBB0_896:
	s_or_b64 exec, exec, s[72:73]
	v_mul_f32_e32 v27, 0x4b800000, v26
	v_cndmask_b32_e64 v26, v26, v27, s[12:13]
	v_rsq_f32_e32 v26, v26
	s_nop 0
	v_mul_f32_e32 v27, 0x45800000, v26
	v_cndmask_b32_e64 v26, v26, v27, s[12:13]
	v_mul_f32_e32 v24, v24, v26
	v_mul_f32_e32 v24, v24, v120
	s_nop 1
	v_mov_b32_dpp v27, v24 quad_perm:[1,0,3,2] row_mask:0xf bank_mask:0xf
	s_and_saveexec_b64 s[12:13], s[10:11]
	s_cbranch_execz .LBB0_898
	s_waitcnt lgkmcnt(0)
	v_add_co_u32_e32 v34, vcc, 0x11000, v48
	v_cvt_pk_bf16_f32 v24, v24, v27
	s_nop 1
	v_addc_co_u32_e32 v35, vcc, 0, v49, vcc
	global_store_dword v[34:35], v24, off
.LBB0_898:
	s_or_b64 exec, exec, s[12:13]
	v_mul_f32_e32 v24, v25, v26
	v_mul_f32_e32 v24, v24, v119
	s_nop 1
	v_mov_b32_dpp v25, v24 quad_perm:[1,0,3,2] row_mask:0xf bank_mask:0xf
	s_and_saveexec_b64 s[12:13], s[10:11]
	s_cbranch_execz .LBB0_900
	s_waitcnt lgkmcnt(0)
	v_cvt_pk_bf16_f32 v27, v24, v25
	v_add_co_u32_e32 v24, vcc, 0x11000, v48
	s_nop 1
	v_addc_co_u32_e32 v25, vcc, 0, v49, vcc
	global_store_dword v[24:25], v27, off offset:64
.LBB0_900:
	s_or_b64 exec, exec, s[12:13]
	v_mul_f32_e32 v21, v21, v26
	v_mul_f32_e32 v21, v21, v118
	s_nop 1
	v_mov_b32_dpp v24, v21 quad_perm:[1,0,3,2] row_mask:0xf bank_mask:0xf
	s_and_saveexec_b64 s[12:13], s[10:11]
	s_cbranch_execz .LBB0_902
	s_waitcnt lgkmcnt(0)
	v_cvt_pk_bf16_f32 v21, v21, v24
	v_add_co_u32_e32 v24, vcc, 0x11000, v48
	s_nop 1
	v_addc_co_u32_e32 v25, vcc, 0, v49, vcc
	global_store_dword v[24:25], v21, off offset:128
; __device__ __forceinline__ unsigned cvt_pk_bf16(float lo, float hi) { unsigned r; asm volatile("v_cvt_pk_bf16_f32 %0, %1, %2" : "=v"(r) : "v"(lo), "v"(hi)); return r; }
; __device__ __forceinline__ int crow(int r, int hi) { return (r & 3) + 8 * (r >> 2) + 4 * hi; }
; __device__ __forceinline__ bool fox_block(const BlockRef& cur, BlockRef& nxt, unsigned* ctr, const unsigned* nrm, bf16_t* PROJ, bf16_t* MIX, char* lds, Seam& S, const float* __restrict__ CF, const float* __restrict__ fnorm) {
;     ...
;         rs[r] = rsqrtf(a * (1.f / 128.f) + RMS_EPS); }
;     ...
;     for (int r = 0; r < 16; ++r) { const int orow = crow(r, hi);
; #pragma unroll
;         for (int d0 = 0; d0 < 4; ++d0) { const float v = o[d0][r] * rs[r] * gn[d0];
;             const float vn = __shfl_xor(v, 1);
;             if ((r32 & 1) == 0) *(unsigned*)(Ow + (size_t)orow * DM + d0 * 32 + r32) = cvt_pk_bf16(v, vn); } }
.LBB0_902:
	s_or_b64 exec, exec, s[12:13]
	v_mul_f32_e32 v20, v20, v26
	v_mul_f32_e32 v20, v20, v95
	s_nop 1
	v_mov_b32_dpp v21, v20 quad_perm:[1,0,3,2] row_mask:0xf bank_mask:0xf
	s_and_saveexec_b64 s[12:13], s[10:11]
	s_cbranch_execz .LBB0_904
	s_waitcnt lgkmcnt(0)
	v_cvt_pk_bf16_f32 v24, v20, v21
	v_add_co_u32_e32 v20, vcc, 0x11000, v48
	s_nop 1
	v_addc_co_u32_e32 v21, vcc, 0, v49, vcc
	global_store_dword v[20:21], v24, off offset:192
.LBB0_904:
	s_or_b64 exec, exec, s[12:13]
	v_pk_add_f32 v[12:13], v[12:13], v[22:23]
	s_nop 0
	v_pk_fma_f32 v[12:13], v[12:13], s[48:49], v[198:199] op_sel_hi:[1,0,0]
	s_nop 0
	v_mul_f32_e32 v20, 0x4b800000, v13
	v_cmp_gt_f32_e32 vcc, s44, v13
	v_cmp_gt_f32_e64 s[12:13], s44, v12
	s_nop 0
	v_cndmask_b32_e32 v13, v13, v20, vcc
	v_rsq_f32_e32 v13, v13
	s_nop 0
	v_mul_f32_e32 v20, 0x45800000, v13
	v_cndmask_b32_e32 v13, v13, v20, vcc
	v_mul_f32_e32 v18, v18, v13
	v_mul_f32_e32 v18, v18, v120
	s_nop 1
	v_mov_b32_dpp v20, v18 quad_perm:[1,0,3,2] row_mask:0xf bank_mask:0xf
	s_and_saveexec_b64 s[72:73], s[10:11]
	s_cbranch_execz .LBB0_906
	s_waitcnt lgkmcnt(0)
	v_cvt_pk_bf16_f32 v18, v18, v20
	v_add_co_u32_e32 v20, vcc, 0x12000, v48
	s_nop 1
	v_addc_co_u32_e32 v21, vcc, 0, v49, vcc
	global_store_dword v[20:21], v18, off
.LBB0_906:
	s_or_b64 exec, exec, s[72:73]
	v_mul_f32_e32 v18, v19, v13
	v_mul_f32_e32 v18, v18, v119
	s_nop 1
	v_mov_b32_dpp v19, v18 quad_perm:[1,0,3,2] row_mask:0xf bank_mask:0xf
	s_and_saveexec_b64 s[72:73], s[10:11]
	s_cbranch_execz .LBB0_908
	s_waitcnt lgkmcnt(0)
	v_cvt_pk_bf16_f32 v20, v18, v19
	v_add_co_u32_e32 v18, vcc, 0x12000, v48
	s_nop 1
	v_addc_co_u32_e32 v19, vcc, 0, v49, vcc
	global_store_dword v[18:19], v20, off offset:64
.LBB0_908:
	s_or_b64 exec, exec, s[72:73]
	v_mul_f32_e32 v11, v11, v13
	v_mul_f32_e32 v11, v11, v118
	s_nop 1
	v_mov_b32_dpp v18, v11 quad_perm:[1,0,3,2] row_mask:0xf bank_mask:0xf
	s_and_saveexec_b64 s[72:73], s[10:11]
	s_cbranch_execz .LBB0_910
	s_waitcnt lgkmcnt(0)
	v_cvt_pk_bf16_f32 v11, v11, v18
	v_add_co_u32_e32 v18, vcc, 0x12000, v48
	s_nop 1
	v_addc_co_u32_e32 v19, vcc, 0, v49, vcc
	global_store_dword v[18:19], v11, off offset:128
.LBB0_910:
	s_or_b64 exec, exec, s[72:73]
	v_mul_f32_e32 v10, v10, v13
	v_mul_f32_e32 v10, v10, v95
	s_nop 1
	v_mov_b32_dpp v11, v10 quad_perm:[1,0,3,2] row_mask:0xf bank_mask:0xf
	s_and_saveexec_b64 s[72:73], s[10:11]
	s_cbranch_execz .LBB0_912
	s_waitcnt lgkmcnt(0)
	v_cvt_pk_bf16_f32 v13, v10, v11
	v_add_co_u32_e32 v10, vcc, 0x12000, v48
	s_nop 1
	v_addc_co_u32_e32 v11, vcc, 0, v49, vcc
	global_store_dword v[10:11], v13, off offset:192
.LBB0_912:
	s_or_b64 exec, exec, s[72:73]
	v_mul_f32_e32 v10, 0x4b800000, v12
	v_cndmask_b32_e64 v10, v12, v10, s[12:13]
	v_rsq_f32_e32 v10, v10
	s_waitcnt lgkmcnt(0)
	v_mul_f32_e32 v11, 0x45800000, v10
	v_cndmask_b32_e64 v10, v10, v11, s[12:13]
	v_mul_f32_e32 v8, v8, v10
	v_mul_f32_e32 v8, v8, v120
	s_nop 1
	v_mov_b32_dpp v11, v8 quad_perm:[1,0,3,2] row_mask:0xf bank_mask:0xf
	s_and_saveexec_b64 s[12:13], s[10:11]
	s_cbranch_execz .LBB0_914
	v_add_co_u32_e32 v12, vcc, 0x13000, v48
	s_waitcnt lgkmcnt(0)
	v_cvt_pk_bf16_f32 v8, v8, v11
	s_nop 0
	v_addc_co_u32_e32 v13, vcc, 0, v49, vcc
	global_store_dword v[12:13], v8, off
.LBB0_914:
	s_or_b64 exec, exec, s[12:13]
	v_mul_f32_e32 v8, v9, v10
	v_mul_f32_e32 v8, v8, v119
	s_nop 1
	v_mov_b32_dpp v9, v8 quad_perm:[1,0,3,2] row_mask:0xf bank_mask:0xf
	s_and_saveexec_b64 s[12:13], s[10:11]
	s_cbranch_execz .LBB0_916
	s_waitcnt lgkmcnt(0)
	v_cvt_pk_bf16_f32 v11, v8, v9
	v_add_co_u32_e32 v8, vcc, 0x13000, v48
	s_nop 1
	v_addc_co_u32_e32 v9, vcc, 0, v49, vcc
	global_store_dword v[8:9], v11, off offset:64
.LBB0_916:
	s_or_b64 exec, exec, s[12:13]
	v_mul_f32_e32 v7, v7, v10
	v_mul_f32_e32 v7, v7, v118
	s_nop 1
	v_mov_b32_dpp v8, v7 quad_perm:[1,0,3,2] row_mask:0xf bank_mask:0xf
	s_and_saveexec_b64 s[12:13], s[10:11]
	s_cbranch_execz .LBB0_918
	s_waitcnt lgkmcnt(0)
	v_cvt_pk_bf16_f32 v7, v7, v8
	v_add_co_u32_e32 v8, vcc, 0x13000, v48
	s_nop 1
	v_addc_co_u32_e32 v9, vcc, 0, v49, vcc
	global_store_dword v[8:9], v7, off offset:128
.LBB0_918:
	s_or_b64 exec, exec, s[12:13]
	v_mul_f32_e32 v6, v6, v10
	v_mul_f32_e32 v6, v6, v95
	s_nop 1
	v_mov_b32_dpp v7, v6 quad_perm:[1,0,3,2] row_mask:0xf bank_mask:0xf
	s_and_saveexec_b64 s[12:13], s[10:11]
	s_cbranch_execz .LBB0_920
	s_waitcnt lgkmcnt(0)
	v_cvt_pk_bf16_f32 v8, v6, v7
	v_add_co_u32_e32 v6, vcc, 0x13000, v48
	s_nop 1
	v_addc_co_u32_e32 v7, vcc, 0, v49, vcc
	global_store_dword v[6:7], v8, off offset:192
.LBB0_920:
	s_or_b64 exec, exec, s[12:13]
	s_waitcnt lgkmcnt(0)
	v_pk_add_f32 v[6:7], v[46:47], v[62:63]
	s_nop 0
	v_pk_fma_f32 v[6:7], v[6:7], s[48:49], v[198:199] op_sel_hi:[1,0,0]
	s_nop 0
	v_mul_f32_e32 v8, 0x4b800000, v7
	v_cmp_gt_f32_e32 vcc, s44, v7
	v_cmp_gt_f32_e64 s[12:13], s44, v6
	s_nop 0
	v_cndmask_b32_e32 v7, v7, v8, vcc
	v_rsq_f32_e32 v7, v7
	s_nop 0
	v_mul_f32_e32 v8, 0x45800000, v7
	v_cndmask_b32_e32 v7, v7, v8, vcc
	v_mul_f32_e32 v8, v60, v7
	v_mul_f32_e32 v8, v8, v120
	s_nop 1
	v_mov_b32_dpp v9, v8 quad_perm:[1,0,3,2] row_mask:0xf bank_mask:0xf
	s_and_saveexec_b64 s[72:73], s[10:11]
	s_cbranch_execz .LBB0_922
	s_waitcnt lgkmcnt(0)
	v_cvt_pk_bf16_f32 v10, v8, v9
	v_add_co_u32_e32 v8, vcc, 0x18000, v48
	s_nop 1
	v_addc_co_u32_e32 v9, vcc, 0, v49, vcc
	global_store_dword v[8:9], v10, off
.LBB0_922:
	s_or_b64 exec, exec, s[72:73]
	v_mul_f32_e32 v8, v61, v7
	v_mul_f32_e32 v8, v8, v119
	s_waitcnt lgkmcnt(0)
	s_nop 1
	v_mov_b32_dpp v9, v8 quad_perm:[1,0,3,2] row_mask:0xf bank_mask:0xf
	s_and_saveexec_b64 s[72:73], s[10:11]
	s_cbranch_execz .LBB0_924
	s_waitcnt lgkmcnt(0)
	v_cvt_pk_bf16_f32 v10, v8, v9
	v_add_co_u32_e32 v8, vcc, 0x18000, v48
	s_nop 1
	v_addc_co_u32_e32 v9, vcc, 0, v49, vcc
	global_store_dword v[8:9], v10, off offset:64
; __device__ __forceinline__ unsigned cvt_pk_bf16(float lo, float hi) { unsigned r; asm volatile("v_cvt_pk_bf16_f32 %0, %1, %2" : "=v"(r) : "v"(lo), "v"(hi)); return r; }
; __device__ __forceinline__ int crow(int r, int hi) { return (r & 3) + 8 * (r >> 2) + 4 * hi; }
; __device__ __forceinline__ bool fox_block(const BlockRef& cur, BlockRef& nxt, unsigned* ctr, const unsigned* nrm, bf16_t* PROJ, bf16_t* MIX, char* lds, Seam& S, const float* __restrict__ CF, const float* __restrict__ fnorm) {
;     ...
;         rs[r] = rsqrtf(a * (1.f / 128.f) + RMS_EPS); }
;     ...
;     for (int r = 0; r < 16; ++r) { const int orow = crow(r, hi);
; #pragma unroll
;         for (int d0 = 0; d0 < 4; ++d0) { const float v = o[d0][r] * rs[r] * gn[d0];
;             const float vn = __shfl_xor(v, 1);
;             if ((r32 & 1) == 0) *(unsigned*)(Ow + (size_t)orow * DM + d0 * 32 + r32) = cvt_pk_bf16(v, vn); } }
.LBB0_924:
	s_or_b64 exec, exec, s[72:73]
	v_mul_f32_e32 v8, v59, v7
	v_mul_f32_e32 v8, v8, v118
	s_waitcnt lgkmcnt(0)
	s_nop 1
	v_mov_b32_dpp v9, v8 quad_perm:[1,0,3,2] row_mask:0xf bank_mask:0xf
	s_and_saveexec_b64 s[72:73], s[10:11]
	s_cbranch_execz .LBB0_926
	s_waitcnt lgkmcnt(0)
	v_cvt_pk_bf16_f32 v10, v8, v9
	v_add_co_u32_e32 v8, vcc, 0x18000, v48
	s_nop 1
	v_addc_co_u32_e32 v9, vcc, 0, v49, vcc
	global_store_dword v[8:9], v10, off offset:128
.LBB0_926:
	s_or_b64 exec, exec, s[72:73]
	v_mul_f32_e32 v7, v58, v7
	v_mul_f32_e32 v7, v7, v95
	s_nop 1
	v_mov_b32_dpp v8, v7 quad_perm:[1,0,3,2] row_mask:0xf bank_mask:0xf
	s_and_saveexec_b64 s[72:73], s[10:11]
	s_cbranch_execz .LBB0_928
	s_waitcnt lgkmcnt(0)
	v_cvt_pk_bf16_f32 v7, v7, v8
	v_add_co_u32_e32 v8, vcc, 0x18000, v48
	s_nop 1
	v_addc_co_u32_e32 v9, vcc, 0, v49, vcc
	global_store_dword v[8:9], v7, off offset:192
.LBB0_928:
	s_or_b64 exec, exec, s[72:73]
	v_mul_f32_e32 v7, 0x4b800000, v6
	v_cndmask_b32_e64 v6, v6, v7, s[12:13]
	v_rsq_f32_e32 v6, v6
	s_nop 0
	v_mul_f32_e32 v7, 0x45800000, v6
	v_cndmask_b32_e64 v6, v6, v7, s[12:13]
	v_mul_f32_e32 v7, v44, v6
	v_mul_f32_e32 v7, v120, v7
	s_waitcnt lgkmcnt(0)
	s_nop 1
	v_mov_b32_dpp v8, v7 quad_perm:[1,0,3,2] row_mask:0xf bank_mask:0xf
	s_and_saveexec_b64 s[12:13], s[10:11]
	s_cbranch_execz .LBB0_930
	s_waitcnt lgkmcnt(0)
	v_cvt_pk_bf16_f32 v7, v7, v8
	v_add_co_u32_e32 v8, vcc, 0x19000, v48
	s_nop 1
	v_addc_co_u32_e32 v9, vcc, 0, v49, vcc
	global_store_dword v[8:9], v7, off
.LBB0_930:
	s_or_b64 exec, exec, s[12:13]
	v_mul_f32_e32 v7, v45, v6
	v_mul_f32_e32 v7, v119, v7
	s_waitcnt lgkmcnt(0)
	s_nop 1
	v_mov_b32_dpp v8, v7 quad_perm:[1,0,3,2] row_mask:0xf bank_mask:0xf
	s_and_saveexec_b64 s[12:13], s[10:11]
	s_cbranch_execz .LBB0_932
	s_waitcnt lgkmcnt(0)
	v_cvt_pk_bf16_f32 v7, v7, v8
	v_add_co_u32_e32 v8, vcc, 0x19000, v48
	s_nop 1
	v_addc_co_u32_e32 v9, vcc, 0, v49, vcc
	global_store_dword v[8:9], v7, off offset:64
.LBB0_932:
	s_or_b64 exec, exec, s[12:13]
	v_mul_f32_e32 v7, v31, v6
	v_mul_f32_e32 v7, v7, v118
	s_waitcnt lgkmcnt(0)
	s_nop 1
	v_mov_b32_dpp v8, v7 quad_perm:[1,0,3,2] row_mask:0xf bank_mask:0xf
	s_and_saveexec_b64 s[12:13], s[10:11]
	s_cbranch_execz .LBB0_934
	s_waitcnt lgkmcnt(0)
	v_cvt_pk_bf16_f32 v7, v7, v8
	v_add_co_u32_e32 v8, vcc, 0x19000, v48
	s_nop 1
	v_addc_co_u32_e32 v9, vcc, 0, v49, vcc
	global_store_dword v[8:9], v7, off offset:128
.LBB0_934:
	s_or_b64 exec, exec, s[12:13]
	v_mul_f32_e32 v6, v30, v6
	v_mul_f32_e32 v6, v6, v95
	s_nop 1
	v_mov_b32_dpp v7, v6 quad_perm:[1,0,3,2] row_mask:0xf bank_mask:0xf
	s_and_saveexec_b64 s[12:13], s[10:11]
	s_cbranch_execz .LBB0_936
	s_waitcnt lgkmcnt(0)
	v_cvt_pk_bf16_f32 v8, v6, v7
	v_add_co_u32_e32 v6, vcc, 0x19000, v48
	s_nop 1
	v_addc_co_u32_e32 v7, vcc, 0, v49, vcc
	global_store_dword v[6:7], v8, off offset:192
.LBB0_936:
	s_or_b64 exec, exec, s[12:13]
	s_waitcnt lgkmcnt(0)
	v_pk_add_f32 v[6:7], v[16:17], v[32:33]
	s_nop 0
	v_pk_fma_f32 v[6:7], v[6:7], s[48:49], v[198:199] op_sel_hi:[1,0,0]
	s_nop 0
	v_mul_f32_e32 v8, 0x4b800000, v7
	v_cmp_gt_f32_e32 vcc, s44, v7
	v_cmp_gt_f32_e64 s[12:13], s44, v6
	s_nop 0
	v_cndmask_b32_e32 v7, v7, v8, vcc
	v_rsq_f32_e32 v7, v7
	s_nop 0
	v_mul_f32_e32 v8, 0x45800000, v7
	v_cndmask_b32_e32 v7, v7, v8, vcc
	v_mul_f32_e32 v8, v28, v7
	v_mul_f32_e32 v8, v120, v8
	s_nop 1
	v_mov_b32_dpp v9, v8 quad_perm:[1,0,3,2] row_mask:0xf bank_mask:0xf
	s_and_saveexec_b64 s[72:73], s[10:11]
	s_cbranch_execz .LBB0_938
	s_waitcnt lgkmcnt(0)
	v_cvt_pk_bf16_f32 v10, v8, v9
	v_add_co_u32_e32 v8, vcc, 0x1a000, v48
	s_nop 1
	v_addc_co_u32_e32 v9, vcc, 0, v49, vcc
	global_store_dword v[8:9], v10, off
.LBB0_938:
	s_or_b64 exec, exec, s[72:73]
	v_mul_f32_e32 v8, v29, v7
	v_mul_f32_e32 v8, v119, v8
	s_waitcnt lgkmcnt(0)
	s_nop 1
	v_mov_b32_dpp v9, v8 quad_perm:[1,0,3,2] row_mask:0xf bank_mask:0xf
	s_and_saveexec_b64 s[72:73], s[10:11]
	s_cbranch_execz .LBB0_940
	s_waitcnt lgkmcnt(0)
	v_cvt_pk_bf16_f32 v10, v8, v9
	v_add_co_u32_e32 v8, vcc, 0x1a000, v48
	s_nop 1
	v_addc_co_u32_e32 v9, vcc, 0, v49, vcc
	global_store_dword v[8:9], v10, off offset:64
.LBB0_940:
	s_or_b64 exec, exec, s[72:73]
	v_mul_f32_e32 v8, v15, v7
	v_mul_f32_e32 v8, v118, v8
	s_waitcnt lgkmcnt(0)
	s_nop 1
	v_mov_b32_dpp v9, v8 quad_perm:[1,0,3,2] row_mask:0xf bank_mask:0xf
	s_and_saveexec_b64 s[72:73], s[10:11]
	s_cbranch_execz .LBB0_942
	s_waitcnt lgkmcnt(0)
	v_cvt_pk_bf16_f32 v10, v8, v9
	v_add_co_u32_e32 v8, vcc, 0x1a000, v48
	s_nop 1
	v_addc_co_u32_e32 v9, vcc, 0, v49, vcc
	global_store_dword v[8:9], v10, off offset:128
.LBB0_942:
	s_or_b64 exec, exec, s[72:73]
	v_mul_f32_e32 v7, v14, v7
	v_mul_f32_e32 v7, v95, v7
	s_nop 1
	v_mov_b32_dpp v8, v7 quad_perm:[1,0,3,2] row_mask:0xf bank_mask:0xf
	s_and_saveexec_b64 s[72:73], s[10:11]
	s_cbranch_execz .LBB0_944
	s_waitcnt lgkmcnt(0)
	v_cvt_pk_bf16_f32 v7, v7, v8
	v_add_co_u32_e32 v8, vcc, 0x1a000, v48
	s_nop 1
	v_addc_co_u32_e32 v9, vcc, 0, v49, vcc
	global_store_dword v[8:9], v7, off offset:192
.LBB0_944:
	s_or_b64 exec, exec, s[72:73]
	v_mul_f32_e32 v7, 0x4b800000, v6
	v_cndmask_b32_e64 v6, v6, v7, s[12:13]
	v_rsq_f32_e32 v6, v6
	s_nop 0
	v_mul_f32_e32 v7, 0x45800000, v6
	v_cndmask_b32_e64 v6, v6, v7, s[12:13]
	v_mul_f32_e32 v4, v4, v6
	v_mul_f32_e32 v4, v120, v4
	s_nop 1
	v_mov_b32_dpp v7, v4 quad_perm:[1,0,3,2] row_mask:0xf bank_mask:0xf
	s_and_saveexec_b64 s[12:13], s[10:11]
	s_cbranch_execz .LBB0_946
	s_waitcnt lgkmcnt(0)
	v_add_co_u32_e32 v8, vcc, 0x1b000, v48
	v_cvt_pk_bf16_f32 v4, v4, v7
	s_nop 1
	v_addc_co_u32_e32 v9, vcc, 0, v49, vcc
	global_store_dword v[8:9], v4, off
.LBB0_946:
	s_or_b64 exec, exec, s[12:13]
	v_mul_f32_e32 v4, v5, v6
	v_mul_f32_e32 v4, v119, v4
	s_nop 1
	v_mov_b32_dpp v5, v4 quad_perm:[1,0,3,2] row_mask:0xf bank_mask:0xf
	s_and_saveexec_b64 s[12:13], s[10:11]
	s_cbranch_execz .LBB0_948
	s_waitcnt lgkmcnt(0)
	v_cvt_pk_bf16_f32 v7, v4, v5
	v_add_co_u32_e32 v4, vcc, 0x1b000, v48
	s_nop 1
	v_addc_co_u32_e32 v5, vcc, 0, v49, vcc
	global_store_dword v[4:5], v7, off offset:64
.LBB0_948:
	s_or_b64 exec, exec, s[12:13]
	v_mul_f32_e32 v3, v3, v6
	v_mul_f32_e32 v3, v118, v3
	s_nop 1
	v_mov_b32_dpp v4, v3 quad_perm:[1,0,3,2] row_mask:0xf bank_mask:0xf
	s_and_saveexec_b64 s[12:13], s[10:11]
	s_cbranch_execz .LBB0_950
	s_waitcnt lgkmcnt(0)
	v_cvt_pk_bf16_f32 v3, v3, v4
	v_add_co_u32_e32 v4, vcc, 0x1b000, v48
	s_nop 1
	v_addc_co_u32_e32 v5, vcc, 0, v49, vcc
	global_store_dword v[4:5], v3, off offset:128
.LBB0_950:
	s_or_b64 exec, exec, s[12:13]
	v_mul_f32_e32 v2, v2, v6
	v_mul_f32_e32 v2, v95, v2
	s_nop 1
	v_mov_b32_dpp v3, v2 quad_perm:[1,0,3,2] row_mask:0xf bank_mask:0xf
	s_and_saveexec_b64 s[12:13], s[10:11]
	s_cbranch_execz .LBB0_952
	s_waitcnt lgkmcnt(0)
	v_cvt_pk_bf16_f32 v4, v2, v3
	v_add_co_u32_e32 v2, vcc, 0x1b000, v48
	s_nop 1
	v_addc_co_u32_e32 v3, vcc, 0, v49, vcc
	global_store_dword v[2:3], v4, off offset:192

; #define SBAR() __builtin_amdgcn_sched_barrier(0)
; __device__ __forceinline__ int crow(int r, int hi) { return (r & 3) + 8 * (r >> 2) + 4 * hi; }
; #define SEAM_K0() do { VMWN(8); SWRITE_HK(0); SBAR(); } while (0)
; __device__ __forceinline__ bool fox_block(const BlockRef& cur, BlockRef& nxt, unsigned* ctr, const unsigned* nrm, bf16_t* PROJ, bf16_t* MIX, char* lds, Seam& S, const float* __restrict__ CF, const float* __restrict__ fnorm) {
;     ...
;     SBAR(); SEAM_K0();
;     if (hi == 0) li_l[r32] = l_reg; asm volatile("s_waitcnt lgkmcnt(0)" ::: "memory");
;     float rs[16];
; #pragma unroll
;     for (int r = 0; r < 16; ++r) { const float rl = __builtin_amdgcn_rcpf(li_l[crow(r, hi)]); float a = 0.f;
; #pragma unroll
;         for (int d0 = 0; d0 < 4; ++d0) { const float v = o[d0][r] * rl; o[d0][r] = v; a += v * v; }
;         a += __shfl_xor(a, 1); a += __shfl_xor(a, 2); a += __shfl_xor(a, 4); a += __shfl_xor(a, 8); a += __shfl_xor(a, 16);
;         rs[r] = rsqrtf(a * (1.f / 128.f) + RMS_EPS); }
.LBB0_2250:
	s_ashr_i32 s73, s72, 31
	s_waitcnt vmcnt(8)
	s_waitcnt vmcnt(0) lgkmcnt(0)
	ds_write_b128 v213, v[102:105] offset:32768
	ds_write_b128 v213, v[110:113] offset:40960
	v_cmp_gt_u32_e32 vcc, 32, v214
	s_and_saveexec_b64 s[10:11], vcc
	ds_write_b32 v215, v114
	s_or_b64 exec, exec, s[10:11]
	v_and_b32_e32 v67, 64, v207
	v_xor_b32_e32 v66, 1, v207
	v_add_u32_e32 v67, 64, v67
	v_cmp_lt_i32_e32 vcc, v66, v67
	s_waitcnt lgkmcnt(0)
	v_mov_b32_e32 v74, v50
	v_mov_b32_e32 v75, v34
	v_cndmask_b32_e32 v66, v207, v66, vcc
	v_lshlrev_b32_e32 v116, 2, v66
	v_xor_b32_e32 v66, 2, v207
	v_cmp_lt_i32_e32 vcc, v66, v67
	v_mov_b32_e32 v34, v51
	v_lshl_or_b32 v196, s22, 7, v211
	v_cndmask_b32_e32 v66, v207, v66, vcc
	v_lshlrev_b32_e32 v118, 2, v66
	v_xor_b32_e32 v66, 4, v207
	v_cmp_lt_i32_e32 vcc, v66, v67
	s_nop 1
	v_cndmask_b32_e32 v66, v207, v66, vcc
	v_lshlrev_b32_e32 v119, 2, v66
	v_xor_b32_e32 v66, 8, v207
	v_cmp_lt_i32_e32 vcc, v66, v67
	s_nop 1
	v_cndmask_b32_e32 v66, v207, v66, vcc
	v_lshlrev_b32_e32 v120, 2, v66
	v_xor_b32_e32 v66, 16, v207
	v_cmp_lt_i32_e32 vcc, v66, v67
	s_nop 1
	v_cndmask_b32_e32 v66, v207, v66, vcc
	v_lshlrev_b32_e32 v121, 2, v66
	ds_read_b128 v[70:73], v212
	ds_read_b128 v[66:69], v212 offset:32
	s_waitcnt lgkmcnt(0)
	v_rcp_f32_e32 v70, v70
	s_nop 0
	v_pk_mul_f32 v[86:87], v[74:75], v[70:71] op_sel_hi:[1,0]
	v_mov_b32_e32 v74, v2
	v_rcp_f32_e32 v2, v71
	v_mov_b32_e32 v75, v18
	v_mov_b32_e32 v18, v3
	v_pk_mul_f32 v[76:77], v[86:87], v[86:87]
	v_pk_mul_f32 v[80:81], v[34:35], v[2:3] op_sel_hi:[1,0]
	v_pk_mul_f32 v[84:85], v[74:75], v[70:71] op_sel_hi:[1,0]
	v_pk_mul_f32 v[34:35], v[80:81], v[80:81]
	v_pk_mul_f32 v[74:75], v[18:19], v[2:3] op_sel_hi:[1,0]
	v_pk_mul_f32 v[78:79], v[84:85], v[84:85]
	v_pk_mul_f32 v[2:3], v[74:75], v[74:75]
	v_mov_b32_e32 v18, v34
	v_mov_b32_e32 v19, v76
	v_mov_b32_e32 v76, v35
	v_pk_add_f32 v[18:19], v[18:19], v[76:77]
	v_mov_b32_e32 v34, v3
	v_mov_b32_e32 v35, v79
	v_pk_add_f32 v[18:19], v[34:35], v[18:19]
	v_mov_b32_e32 v3, v78
	v_pk_add_f32 v[2:3], v[2:3], v[18:19]
	s_nop 1
	v_mov_b32_dpp v19, v3 quad_perm:[1,0,3,2] row_mask:0xf bank_mask:0xf
	s_nop 1
	v_mov_b32_dpp v18, v2 quad_perm:[1,0,3,2] row_mask:0xf bank_mask:0xf
	v_mov_b32_e32 v34, v4
	v_rcp_f32_e32 v4, v73
	v_mov_b32_e32 v35, v20
	v_mov_b32_e32 v20, v5
	s_waitcnt lgkmcnt(0)
	v_pk_add_f32 v[2:3], v[2:3], v[18:19]
	ds_bpermute_b32 v19, v118, v3
	ds_bpermute_b32 v18, v118, v2
	s_waitcnt lgkmcnt(0)
	v_pk_add_f32 v[2:3], v[2:3], v[18:19]
	ds_bpermute_b32 v19, v119, v3
	ds_bpermute_b32 v18, v119, v2
	s_waitcnt lgkmcnt(0)
	v_pk_add_f32 v[2:3], v[2:3], v[18:19]
	ds_bpermute_b32 v19, v120, v3
	ds_bpermute_b32 v18, v120, v2
	s_waitcnt lgkmcnt(0)
	v_pk_add_f32 v[2:3], v[2:3], v[18:19]
	ds_bpermute_b32 v19, v121, v3
	ds_bpermute_b32 v18, v121, v2
	s_waitcnt lgkmcnt(0)
	v_pk_add_f32 v[2:3], v[2:3], v[18:19]
	s_nop 0
	v_pk_fma_f32 v[94:95], v[2:3], s[48:49], v[198:199] op_sel_hi:[1,0,0]
	v_mov_b32_e32 v18, v52
	v_mul_f32_e32 v2, 0x4b800000, v95
	v_cmp_gt_f32_e64 s[10:11], s44, v95
	v_mov_b32_e32 v19, v36
	v_mov_b32_e32 v36, v53
	v_cndmask_b32_e64 v2, v95, v2, s[10:11]
	v_rsq_f32_e32 v2, v2
	v_pk_mul_f32 v[78:79], v[36:37], v[4:5] op_sel_hi:[1,0]
	v_cmp_gt_f32_e32 vcc, s44, v94
	v_mul_f32_e32 v3, 0x45800000, v2
	v_cndmask_b32_e64 v117, v2, v3, s[10:11]
	v_rcp_f32_e32 v2, v72
	v_pk_mul_f32 v[72:73], v[20:21], v[4:5] op_sel_hi:[1,0]
	s_lshl_b64 s[10:11], s[72:73], 12
	v_pk_mul_f32 v[4:5], v[72:73], v[72:73]
	v_pk_mul_f32 v[88:89], v[18:19], v[2:3] op_sel_hi:[1,0]
	v_pk_mul_f32 v[82:83], v[34:35], v[2:3] op_sel_hi:[1,0]
	v_pk_mul_f32 v[18:19], v[88:89], v[88:89]
	v_pk_mul_f32 v[34:35], v[78:79], v[78:79]
	v_pk_mul_f32 v[2:3], v[82:83], v[82:83]
	v_mov_b32_e32 v20, v34
	v_mov_b32_e32 v21, v18
	v_mov_b32_e32 v18, v35
	v_pk_add_f32 v[18:19], v[20:21], v[18:19]
	v_mov_b32_e32 v20, v5
	v_mov_b32_e32 v21, v3
	v_pk_add_f32 v[18:19], v[20:21], v[18:19]
	v_mov_b32_e32 v5, v2
	v_pk_add_f32 v[2:3], v[4:5], v[18:19]
	s_nop 1
	v_mov_b32_dpp v5, v3 quad_perm:[1,0,3,2] row_mask:0xf bank_mask:0xf
	s_nop 1
	v_mov_b32_dpp v4, v2 quad_perm:[1,0,3,2] row_mask:0xf bank_mask:0xf
	v_mov_b32_e32 v18, v6
	v_rcp_f32_e32 v6, v67
	v_mov_b32_e32 v19, v22
	v_mov_b32_e32 v22, v7
	s_waitcnt lgkmcnt(0)
	v_pk_add_f32 v[2:3], v[2:3], v[4:5]
	ds_bpermute_b32 v5, v118, v3
	ds_bpermute_b32 v4, v118, v2
	v_pk_mul_f32 v[50:51], v[22:23], v[6:7] op_sel_hi:[1,0]
	s_add_u32 s12, s70, s10
	s_addc_u32 s13, s71, s11
	s_waitcnt lgkmcnt(0)
	v_pk_add_f32 v[2:3], v[2:3], v[4:5]
	ds_bpermute_b32 v5, v119, v3
	ds_bpermute_b32 v4, v119, v2
	s_waitcnt lgkmcnt(0)
	v_pk_add_f32 v[2:3], v[2:3], v[4:5]
	ds_bpermute_b32 v5, v120, v3
	ds_bpermute_b32 v4, v120, v2
	s_waitcnt lgkmcnt(0)
	v_pk_add_f32 v[96:97], v[2:3], v[4:5]
	v_rcp_f32_e32 v2, v66
	v_mov_b32_e32 v4, v54
	v_mov_b32_e32 v5, v38
	v_mov_b32_e32 v38, v55
	v_pk_mul_f32 v[76:77], v[4:5], v[2:3] op_sel_hi:[1,0]
	v_pk_mul_f32 v[54:55], v[38:39], v[6:7] op_sel_hi:[1,0]
	v_pk_mul_f32 v[4:5], v[76:77], v[76:77]
	v_pk_mul_f32 v[70:71], v[18:19], v[2:3] op_sel_hi:[1,0]
	v_pk_mul_f32 v[18:19], v[54:55], v[54:55]
	v_pk_mul_f32 v[2:3], v[70:71], v[70:71]
	v_pk_mul_f32 v[6:7], v[50:51], v[50:51]
	v_mov_b32_e32 v20, v18
	v_mov_b32_e32 v21, v4
	v_mov_b32_e32 v4, v19
	v_pk_add_f32 v[4:5], v[20:21], v[4:5]
	v_mov_b32_e32 v18, v7
	v_mov_b32_e32 v19, v3
	v_pk_add_f32 v[4:5], v[18:19], v[4:5]
	v_mov_b32_e32 v7, v2
	v_pk_add_f32 v[2:3], v[6:7], v[4:5]
	s_nop 1
	v_mov_b32_dpp v5, v3 quad_perm:[1,0,3,2] row_mask:0xf bank_mask:0xf
	s_nop 1
	v_mov_b32_dpp v4, v2 quad_perm:[1,0,3,2] row_mask:0xf bank_mask:0xf
	v_mov_b32_e32 v6, v8
	v_mov_b32_e32 v7, v24
	v_mov_b32_e32 v24, v9
	ds_bpermute_b32 v115, v121, v97
	s_waitcnt lgkmcnt(0)
; __device__ __forceinline__ int crow(int r, int hi) { return (r & 3) + 8 * (r >> 2) + 4 * hi; }
; __device__ __forceinline__ bool fox_block(const BlockRef& cur, BlockRef& nxt, unsigned* ctr, const unsigned* nrm, bf16_t* PROJ, bf16_t* MIX, char* lds, Seam& S, const float* __restrict__ CF, const float* __restrict__ fnorm) {
;     ...
;     for (int r = 0; r < 16; ++r) { const float rl = __builtin_amdgcn_rcpf(li_l[crow(r, hi)]); float a = 0.f;
; #pragma unroll
;         for (int d0 = 0; d0 < 4; ++d0) { const float v = o[d0][r] * rl; o[d0][r] = v; a += v * v; }
;         a += __shfl_xor(a, 1); a += __shfl_xor(a, 2); a += __shfl_xor(a, 4); a += __shfl_xor(a, 8); a += __shfl_xor(a, 16);
;         rs[r] = rsqrtf(a * (1.f / 128.f) + RMS_EPS); }
	v_pk_add_f32 v[2:3], v[2:3], v[4:5]
	ds_bpermute_b32 v5, v118, v3
	ds_bpermute_b32 v4, v118, v2
	ds_bpermute_b32 v114, v121, v96
	s_waitcnt lgkmcnt(0)
	v_pk_add_f32 v[2:3], v[2:3], v[4:5]
	ds_bpermute_b32 v5, v119, v3
	ds_bpermute_b32 v4, v119, v2
	s_waitcnt lgkmcnt(0)
	v_pk_add_f32 v[2:3], v[2:3], v[4:5]
	ds_bpermute_b32 v5, v120, v3
	ds_bpermute_b32 v4, v120, v2
	s_waitcnt lgkmcnt(0)
	v_pk_add_f32 v[90:91], v[2:3], v[4:5]
	v_rcp_f32_e32 v2, v68
	v_mov_b32_e32 v4, v56
	v_mov_b32_e32 v5, v40
	v_mov_b32_e32 v40, v57
	v_pk_mul_f32 v[52:53], v[6:7], v[2:3] op_sel_hi:[1,0]
	v_rcp_f32_e32 v6, v69
	v_pk_mul_f32 v[66:67], v[4:5], v[2:3] op_sel_hi:[1,0]
	v_pk_mul_f32 v[2:3], v[52:53], v[52:53]
	v_pk_mul_f32 v[4:5], v[66:67], v[66:67]
	v_pk_mul_f32 v[40:41], v[40:41], v[6:7] op_sel_hi:[1,0]
	v_pk_mul_f32 v[36:37], v[24:25], v[6:7] op_sel_hi:[1,0]
	v_pk_mul_f32 v[18:19], v[40:41], v[40:41]
	v_pk_mul_f32 v[6:7], v[36:37], v[36:37]
	v_mov_b32_e32 v8, v18
	v_mov_b32_e32 v9, v4
	v_mov_b32_e32 v4, v19
	v_pk_add_f32 v[4:5], v[8:9], v[4:5]
	v_mov_b32_e32 v8, v7
	v_mov_b32_e32 v9, v3
	v_pk_add_f32 v[4:5], v[8:9], v[4:5]
	v_mov_b32_e32 v7, v2
	v_pk_add_f32 v[2:3], v[6:7], v[4:5]
	s_nop 1
	v_mov_b32_dpp v5, v3 quad_perm:[1,0,3,2] row_mask:0xf bank_mask:0xf
	s_nop 1
	v_mov_b32_dpp v4, v2 quad_perm:[1,0,3,2] row_mask:0xf bank_mask:0xf
	v_mov_b32_e32 v6, v58
	v_mov_b32_e32 v7, v42
	v_mov_b32_e32 v8, v10
	v_mov_b32_e32 v9, v26
	s_waitcnt lgkmcnt(0)
	v_pk_add_f32 v[2:3], v[2:3], v[4:5]
	ds_bpermute_b32 v5, v118, v3
	ds_bpermute_b32 v4, v118, v2
	v_mov_b32_e32 v42, v59
	v_mov_b32_e32 v26, v11
	ds_bpermute_b32 v93, v121, v91
	ds_bpermute_b32 v92, v121, v90
	s_waitcnt lgkmcnt(0)
	v_pk_add_f32 v[2:3], v[2:3], v[4:5]
	ds_bpermute_b32 v5, v119, v3
	ds_bpermute_b32 v4, v119, v2
	s_waitcnt lgkmcnt(0)
	v_pk_add_f32 v[2:3], v[2:3], v[4:5]
	ds_bpermute_b32 v5, v120, v3
	ds_bpermute_b32 v4, v120, v2
	s_waitcnt lgkmcnt(0)
	v_pk_add_f32 v[56:57], v[2:3], v[4:5]
	ds_read_b128 v[2:5], v212 offset:64
	ds_bpermute_b32 v69, v121, v57
	ds_bpermute_b32 v68, v121, v56
	s_waitcnt lgkmcnt(0)
	v_rcp_f32_e32 v2, v2
	s_nop 0
	v_pk_mul_f32 v[38:39], v[6:7], v[2:3] op_sel_hi:[1,0]
	v_pk_mul_f32 v[34:35], v[8:9], v[2:3] op_sel_hi:[1,0]
	v_rcp_f32_e32 v2, v3
	v_pk_mul_f32 v[6:7], v[38:39], v[38:39]
	v_pk_mul_f32 v[8:9], v[34:35], v[34:35]
	v_mov_b32_e32 v11, v6
	v_pk_mul_f32 v[24:25], v[42:43], v[2:3] op_sel_hi:[1,0]
	v_pk_mul_f32 v[20:21], v[26:27], v[2:3] op_sel_hi:[1,0]
	v_pk_mul_f32 v[18:19], v[24:25], v[24:25]
	v_pk_mul_f32 v[2:3], v[20:21], v[20:21]
	v_mov_b32_e32 v10, v18
	v_mov_b32_e32 v6, v19
	v_pk_add_f32 v[6:7], v[10:11], v[6:7]
	v_mov_b32_e32 v10, v3
	v_mov_b32_e32 v11, v9
	v_pk_add_f32 v[6:7], v[10:11], v[6:7]
	v_mov_b32_e32 v3, v8
	v_pk_add_f32 v[2:3], v[2:3], v[6:7]
	s_nop 1
	v_mov_b32_dpp v7, v3 quad_perm:[1,0,3,2] row_mask:0xf bank_mask:0xf
	s_nop 1
	v_mov_b32_dpp v6, v2 quad_perm:[1,0,3,2] row_mask:0xf bank_mask:0xf
	s_waitcnt lgkmcnt(0)
	v_pk_add_f32 v[2:3], v[2:3], v[6:7]
	ds_bpermute_b32 v7, v118, v3
	ds_bpermute_b32 v6, v118, v2
	s_waitcnt lgkmcnt(0)
	v_pk_add_f32 v[2:3], v[2:3], v[6:7]
	ds_bpermute_b32 v7, v119, v3
	ds_bpermute_b32 v6, v119, v2
	s_waitcnt lgkmcnt(0)
	v_pk_add_f32 v[2:3], v[2:3], v[6:7]
	ds_bpermute_b32 v7, v120, v3
	ds_bpermute_b32 v6, v120, v2
	s_waitcnt lgkmcnt(0)
	v_pk_add_f32 v[26:27], v[2:3], v[6:7]
	v_rcp_f32_e32 v2, v4
	v_rcp_f32_e32 v4, v5
	v_mov_b32_e32 v6, v60
	v_mov_b32_e32 v7, v44
	v_mov_b32_e32 v44, v61
	v_pk_mul_f32 v[18:19], v[6:7], v[2:3] op_sel_hi:[1,0]
	v_mov_b32_e32 v6, v12
	v_mov_b32_e32 v7, v28
	v_pk_mul_f32 v[8:9], v[44:45], v[4:5] op_sel_hi:[1,0]
	v_mov_b32_e32 v28, v13
	v_pk_mul_f32 v[22:23], v[18:19], v[18:19]
	v_pk_mul_f32 v[10:11], v[6:7], v[2:3] op_sel_hi:[1,0]
	v_pk_mul_f32 v[44:45], v[8:9], v[8:9]
	v_pk_mul_f32 v[6:7], v[28:29], v[4:5] op_sel_hi:[1,0]
	v_pk_mul_f32 v[2:3], v[10:11], v[10:11]
	v_pk_mul_f32 v[4:5], v[6:7], v[6:7]
	v_mov_b32_e32 v12, v44
	v_mov_b32_e32 v13, v22
	v_mov_b32_e32 v22, v45
	v_pk_add_f32 v[12:13], v[12:13], v[22:23]
	v_mov_b32_e32 v22, v5
	v_mov_b32_e32 v23, v3
	v_pk_add_f32 v[12:13], v[22:23], v[12:13]
	v_mov_b32_e32 v5, v2
	v_pk_add_f32 v[2:3], v[4:5], v[12:13]
	s_nop 1
	v_mov_b32_dpp v5, v3 quad_perm:[1,0,3,2] row_mask:0xf bank_mask:0xf
	s_nop 1
	v_mov_b32_dpp v4, v2 quad_perm:[1,0,3,2] row_mask:0xf bank_mask:0xf
	v_mov_b32_e32 v28, v62
	v_mov_b32_e32 v29, v46
	v_mov_b32_e32 v44, v14
	v_mov_b32_e32 v45, v30
	s_waitcnt lgkmcnt(0)
; __device__ __forceinline__ unsigned cvt_pk_bf16(float lo, float hi) { unsigned r; asm volatile("v_cvt_pk_bf16_f32 %0, %1, %2" : "=v"(r) : "v"(lo), "v"(hi)); return r; }
; __device__ __forceinline__ int crow(int r, int hi) { return (r & 3) + 8 * (r >> 2) + 4 * hi; }
; __device__ __forceinline__ bool fox_block(const BlockRef& cur, BlockRef& nxt, unsigned* ctr, const unsigned* nrm, bf16_t* PROJ, bf16_t* MIX, char* lds, Seam& S, const float* __restrict__ CF, const float* __restrict__ fnorm) {
;     ...
;     for (int r = 0; r < 16; ++r) { const float rl = __builtin_amdgcn_rcpf(li_l[crow(r, hi)]); float a = 0.f;
; #pragma unroll
;         for (int d0 = 0; d0 < 4; ++d0) { const float v = o[d0][r] * rl; o[d0][r] = v; a += v * v; }
;         a += __shfl_xor(a, 1); a += __shfl_xor(a, 2); a += __shfl_xor(a, 4); a += __shfl_xor(a, 8); a += __shfl_xor(a, 16);
;         rs[r] = rsqrtf(a * (1.f / 128.f) + RMS_EPS); }
;     float gn[4];
; #pragma unroll
;     for (int d0 = 0; d0 < 4; ++d0) gn[d0] = fnorm[cur.head * 128 + d0 * 32 + r32];
;     bf16_t* Ow = cur.O + (size_t)(wid * QBLK) * DM;
; #pragma unroll
;     for (int r = 0; r < 16; ++r) { const int orow = crow(r, hi);
; #pragma unroll
;         for (int d0 = 0; d0 < 4; ++d0) { const float v = o[d0][r] * rs[r] * gn[d0];
;             const float vn = __shfl_xor(v, 1);
;             if ((r32 & 1) == 0) *(unsigned*)(Ow + (size_t)orow * DM + d0 * 32 + r32) = cvt_pk_bf16(v, vn); } }
	v_pk_add_f32 v[2:3], v[2:3], v[4:5]
	ds_bpermute_b32 v5, v118, v3
	ds_bpermute_b32 v4, v118, v2
	v_mov_b32_e32 v46, v63
	v_mov_b32_e32 v30, v15
	ds_bpermute_b32 v43, v121, v27
	ds_bpermute_b32 v42, v121, v26
	s_waitcnt lgkmcnt(0)
	v_pk_add_f32 v[2:3], v[2:3], v[4:5]
	ds_bpermute_b32 v5, v119, v3
	ds_bpermute_b32 v4, v119, v2
	s_waitcnt lgkmcnt(0)
	v_pk_add_f32 v[2:3], v[2:3], v[4:5]
	ds_bpermute_b32 v5, v120, v3
	ds_bpermute_b32 v4, v120, v2
	s_waitcnt lgkmcnt(0)
	v_pk_add_f32 v[12:13], v[2:3], v[4:5]
	ds_read_b128 v[2:5], v212 offset:96
	ds_bpermute_b32 v23, v121, v13
	ds_bpermute_b32 v22, v121, v12
	s_waitcnt lgkmcnt(0)
	v_rcp_f32_e32 v2, v2
	s_nop 0
	v_pk_mul_f32 v[60:61], v[28:29], v[2:3] op_sel_hi:[1,0]
	v_pk_mul_f32 v[58:59], v[44:45], v[2:3] op_sel_hi:[1,0]
	v_rcp_f32_e32 v2, v3
	v_pk_mul_f32 v[28:29], v[60:61], v[60:61]
	v_pk_mul_f32 v[122:123], v[58:59], v[58:59]
	v_mov_b32_e32 v15, v28
	v_pk_mul_f32 v[44:45], v[46:47], v[2:3] op_sel_hi:[1,0]
	v_pk_mul_f32 v[30:31], v[30:31], v[2:3] op_sel_hi:[1,0]
	v_pk_mul_f32 v[46:47], v[44:45], v[44:45]
	v_pk_mul_f32 v[2:3], v[30:31], v[30:31]
	v_mov_b32_e32 v14, v46
	v_mov_b32_e32 v28, v47
	v_pk_add_f32 v[14:15], v[14:15], v[28:29]
	v_mov_b32_e32 v28, v3
	v_mov_b32_e32 v29, v123
	v_pk_add_f32 v[14:15], v[28:29], v[14:15]
	v_mov_b32_e32 v3, v122
	v_pk_add_f32 v[2:3], v[2:3], v[14:15]
	s_nop 1
	v_mov_b32_dpp v15, v3 quad_perm:[1,0,3,2] row_mask:0xf bank_mask:0xf
	s_nop 1
	v_mov_b32_dpp v14, v2 quad_perm:[1,0,3,2] row_mask:0xf bank_mask:0xf
	s_waitcnt lgkmcnt(0)
	v_pk_add_f32 v[2:3], v[2:3], v[14:15]
	ds_bpermute_b32 v15, v118, v3
	ds_bpermute_b32 v14, v118, v2
	s_waitcnt lgkmcnt(0)
	v_pk_add_f32 v[2:3], v[2:3], v[14:15]
	ds_bpermute_b32 v15, v119, v3
	ds_bpermute_b32 v14, v119, v2
	s_waitcnt lgkmcnt(0)
	v_pk_add_f32 v[2:3], v[2:3], v[14:15]
	ds_bpermute_b32 v15, v120, v3
	ds_bpermute_b32 v14, v120, v2
	s_waitcnt lgkmcnt(0)
	v_pk_add_f32 v[46:47], v[2:3], v[14:15]
	v_rcp_f32_e32 v2, v4
	v_mov_b32_e32 v14, v64
	v_mov_b32_e32 v15, v48
	v_mov_b32_e32 v48, v65
	v_pk_mul_f32 v[28:29], v[14:15], v[2:3] op_sel_hi:[1,0]
	v_mov_b32_e32 v14, v16
	v_mov_b32_e32 v15, v32
	v_pk_mul_f32 v[14:15], v[14:15], v[2:3] op_sel_hi:[1,0]
	v_rcp_f32_e32 v2, v5
	v_mov_b32_e32 v32, v17
	v_pk_mul_f32 v[122:123], v[28:29], v[28:29]
	v_pk_mul_f32 v[124:125], v[14:15], v[14:15]
	v_pk_mul_f32 v[4:5], v[48:49], v[2:3] op_sel_hi:[1,0]
	v_pk_mul_f32 v[2:3], v[32:33], v[2:3] op_sel_hi:[1,0]
	v_pk_mul_f32 v[48:49], v[4:5], v[4:5]
	v_pk_mul_f32 v[16:17], v[2:3], v[2:3]
	v_mov_b32_e32 v32, v48
	v_mov_b32_e32 v33, v122
	v_mov_b32_e32 v122, v49
	v_pk_add_f32 v[32:33], v[32:33], v[122:123]
	v_mov_b32_e32 v48, v17
	v_mov_b32_e32 v49, v125
	v_pk_add_f32 v[32:33], v[48:49], v[32:33]
	v_mov_b32_e32 v17, v124
	v_pk_add_f32 v[16:17], v[16:17], v[32:33]
	s_nop 1
	v_mov_b32_dpp v33, v17 quad_perm:[1,0,3,2] row_mask:0xf bank_mask:0xf
	s_nop 1
	v_mov_b32_dpp v32, v16 quad_perm:[1,0,3,2] row_mask:0xf bank_mask:0xf
	v_lshl_add_u64 v[48:49], v[196:197], 2, s[60:61]
	v_mul_f32_e32 v64, v86, v117
	ds_bpermute_b32 v63, v121, v47
	ds_bpermute_b32 v62, v121, v46
	s_waitcnt lgkmcnt(0)
	v_pk_add_f32 v[16:17], v[16:17], v[32:33]
	ds_bpermute_b32 v33, v118, v17
	ds_bpermute_b32 v32, v118, v16
	v_lshlrev_b32_e32 v196, 1, v211
	s_waitcnt lgkmcnt(0)
	v_pk_add_f32 v[16:17], v[16:17], v[32:33]
	ds_bpermute_b32 v33, v119, v17
	ds_bpermute_b32 v32, v119, v16
	s_waitcnt lgkmcnt(0)
	v_pk_add_f32 v[16:17], v[16:17], v[32:33]
	ds_bpermute_b32 v33, v120, v17
	ds_bpermute_b32 v32, v120, v16
	flat_load_dword v120, v[48:49]
	flat_load_dword v119, v[48:49] offset:128
	flat_load_dword v118, v[48:49] offset:256
	flat_load_dword v95, v[48:49] offset:384
	v_and_b32_e32 v48, 1, v202
	v_cmp_eq_u32_e64 s[10:11], 0, v48
	v_lshl_add_u64 v[48:49], s[12:13], 0, v[196:197]
	s_waitcnt lgkmcnt(0)
	v_pk_add_f32 v[16:17], v[16:17], v[32:33]
	ds_bpermute_b32 v33, v121, v17
	ds_bpermute_b32 v32, v121, v16
	v_lshlrev_b32_e32 v196, 14, v203
	v_lshl_add_u64 v[48:49], v[48:49], 0, v[196:197]
	s_waitcnt vmcnt(0)
	v_mul_f32_e32 v64, v64, v120
	s_nop 1
	v_mov_b32_dpp v65, v64 quad_perm:[1,0,3,2] row_mask:0xf bank_mask:0xf
	s_and_saveexec_b64 s[12:13], s[10:11]
	s_cbranch_execz .LBB0_2254
	s_waitcnt lgkmcnt(0)
	v_cvt_pk_bf16_f32 v64, v64, v65
	global_store_dword v[48:49], v64, off
